# v14 + dual-accumulator row sums + rescale block moved out of line (common path falls through, no taken branch per step)
# speedup vs baseline: 1.1563x; 1.0001x over previous
.Lat_mainloop:
.Lat_step_M1:
	v_add_u32_e32 v243, s16, v204
	ds_read_b64_tr_b16 v[214:215], v243 offset:24576
	ds_read_b64_tr_b16 v[216:217], v243 offset:25088
	v_mfma_f32_32x32x16_bf16 v[112:127], v[176:179], v[144:147], v[64:79]
	v_add_f32_e32 v245, v80, v81
	v_add_f32_e32 v246, v82, v83
	v_add_f32_e32 v245, v84, v245
	v_add_f32_e32 v246, v85, v246
	v_cvt_pk_bf16_f32 v160, v80, v81
	v_cvt_pk_bf16_f32 v161, v82, v83
	ds_read_b64_tr_b16 v[80:81], v243 offset:28672
	ds_read_b64_tr_b16 v[82:83], v243 offset:29184
	v_mfma_f32_32x32x16_bf16 v[128:143], v[180:183], v[144:147], v[64:79]
	v_add_f32_e32 v245, v86, v245
	v_add_f32_e32 v246, v87, v246
	v_add_f32_e32 v245, v88, v245
	v_add_f32_e32 v246, v89, v246
	v_cvt_pk_bf16_f32 v162, v84, v85
	v_cvt_pk_bf16_f32 v163, v86, v87
	ds_read_b64_tr_b16 v[84:85], v243 offset:25600
	ds_read_b64_tr_b16 v[86:87], v243 offset:26112
	v_mfma_f32_32x32x16_bf16 v[112:127], v[184:187], v[148:151], v[112:127]
	v_add_f32_e32 v245, v90, v245
	v_add_f32_e32 v246, v91, v246
	v_add_f32_e32 v245, v92, v245
	v_add_f32_e32 v246, v93, v246
	v_cvt_pk_bf16_f32 v164, v88, v89
	v_cvt_pk_bf16_f32 v165, v90, v91
	ds_read_b64_tr_b16 v[88:89], v243 offset:29696
	ds_read_b64_tr_b16 v[90:91], v243 offset:30208
	v_mfma_f32_32x32x16_bf16 v[128:143], v[188:191], v[148:151], v[128:143]
	v_add_f32_e32 v245, v94, v245
	v_add_f32_e32 v246, v95, v246
	v_add_f32_e32 v245, v96, v245
	v_add_f32_e32 v246, v97, v246
	v_cvt_pk_bf16_f32 v166, v92, v93
	v_cvt_pk_bf16_f32 v167, v94, v95
	ds_read_b64_tr_b16 v[92:93], v243 offset:26624
	ds_read_b64_tr_b16 v[94:95], v243 offset:27136
	v_mfma_f32_32x32x16_bf16 v[112:127], v[192:195], v[152:155], v[112:127]
	v_add_f32_e32 v245, v98, v245
	v_add_f32_e32 v246, v99, v246
	v_add_f32_e32 v245, v100, v245
	v_add_f32_e32 v246, v101, v246
	v_cvt_pk_bf16_f32 v168, v96, v97
	v_cvt_pk_bf16_f32 v169, v98, v99
	ds_read_b64_tr_b16 v[96:97], v243 offset:30720
	ds_read_b64_tr_b16 v[98:99], v243 offset:31232
	v_mfma_f32_32x32x16_bf16 v[128:143], v[196:199], v[152:155], v[128:143]
	v_add_f32_e32 v245, v102, v245
	v_add_f32_e32 v246, v103, v246
	v_add_f32_e32 v245, v104, v245
	v_add_f32_e32 v246, v105, v246
	v_cvt_pk_bf16_f32 v170, v100, v101
	v_cvt_pk_bf16_f32 v171, v102, v103
	ds_read_b64_tr_b16 v[100:101], v243 offset:27648
	ds_read_b64_tr_b16 v[102:103], v243 offset:28160
	v_mfma_f32_32x32x16_bf16 v[112:127], v[200:203], v[156:159], v[112:127]
	v_add_f32_e32 v245, v106, v245
	v_add_f32_e32 v246, v107, v246
	v_add_f32_e32 v245, v108, v245
	v_add_f32_e32 v246, v109, v246
	v_cvt_pk_bf16_f32 v172, v104, v105
	v_cvt_pk_bf16_f32 v173, v106, v107
	ds_read_b64_tr_b16 v[104:105], v243 offset:31744
	ds_read_b64_tr_b16 v[106:107], v243 offset:32256
	v_mfma_f32_32x32x16_bf16 v[128:143], v[206:209], v[156:159], v[128:143]
	v_add_f32_e32 v245, v110, v245
	v_add_f32_e32 v246, v111, v246
	v_add_f32_e32 v245, v245, v246
	v_cvt_pk_bf16_f32 v174, v108, v109
	v_cvt_pk_bf16_f32 v175, v110, v111
	v_add_f32_e32 v211, v211, v245
	v_add_u32_e32 v244, s18, v219
	s_waitcnt lgkmcnt(8)
	v_mfma_f32_32x32x16_bf16 v[0:15], v[160:163], v[214:217], v[0:15]
	v_max3_f32 v246, v112, v113, v114
	v_max3_f32 v247, v115, v116, v117
	ds_read_b64_tr_b16 v[214:215], v243 offset:49152
	ds_read_b64_tr_b16 v[216:217], v243 offset:49664
	v_mfma_f32_32x32x16_bf16 v[16:31], v[160:163], v[80:83], v[16:31]
	s_add_i32 m0, s17, s54
	v_max3_f32 v246, v246, v118, v119
	v_max3_f32 v247, v247, v120, v121
	v_max3_f32 v246, v246, v122, v123
	v_max3_f32 v247, v247, v124, v125
	ds_read_b64_tr_b16 v[80:81], v243 offset:53248
	ds_read_b64_tr_b16 v[82:83], v243 offset:53760
	global_load_lds_dwordx4 v222, s[0:1]
	s_add_u32 s0, s0, 0x20000
	s_addc_u32 s1, s1, 0
	v_mfma_f32_32x32x16_bf16 v[0:15], v[164:167], v[84:87], v[0:15]
	s_add_i32 s21, s18, s54
	s_add_i32 m0, s21, 0x6000
	v_max3_f32 v246, v246, v126, v127
	v_max3_f32 v247, v247, v128, v129
	v_max3_f32 v246, v246, v130, v131
	v_max3_f32 v247, v247, v132, v133
	ds_read_b64_tr_b16 v[84:85], v243 offset:50176
	ds_read_b64_tr_b16 v[86:87], v243 offset:50688
	global_load_lds_dwordx4 v223, s[4:5]
	v_mfma_f32_32x32x16_bf16 v[16:31], v[164:167], v[88:91], v[16:31]
	s_add_i32 m0, s21, 0xc000
	v_max3_f32 v246, v246, v134, v135
	v_max3_f32 v247, v247, v136, v137
	v_max3_f32 v246, v246, v138, v139
	v_max3_f32 v247, v247, v140, v141
	ds_read_b64_tr_b16 v[88:89], v243 offset:54272
	ds_read_b64_tr_b16 v[90:91], v243 offset:54784
	global_load_lds_dwordx4 v224, s[4:5]
	s_add_u32 s4, s4, 0x20000
	s_addc_u32 s5, s5, 0
	s_waitcnt lgkmcnt(8)
	v_mfma_f32_32x32x16_bf16 v[0:15], v[168:171], v[92:95], v[0:15]
	v_max3_f32 v246, v246, v142, v143
	v_max_f32_e32 v248, v246, v247
	ds_read_b64_tr_b16 v[92:93], v243 offset:51200
	ds_read_b64_tr_b16 v[94:95], v243 offset:51712
	v_cmp_lt_f32_e32 vcc, s87, v248
	s_cbranch_vccnz .Lat_rare_M1
.Lat_cont_M1:
	v_mfma_f32_32x32x16_bf16 v[16:31], v[168:171], v[96:99], v[16:31]
	v_exp_f32_e32 v112, v112
	v_exp_f32_e32 v113, v113
	v_exp_f32_e32 v114, v114
	ds_read_b64_tr_b16 v[96:97], v243 offset:55296
	ds_read_b64_tr_b16 v[98:99], v243 offset:55808
	v_mfma_f32_32x32x16_bf16 v[0:15], v[172:175], v[100:103], v[0:15]
	v_exp_f32_e32 v115, v115
	v_exp_f32_e32 v116, v116
	v_exp_f32_e32 v117, v117
	ds_read_b64_tr_b16 v[100:101], v243 offset:52224
	ds_read_b64_tr_b16 v[102:103], v243 offset:52736
	v_mfma_f32_32x32x16_bf16 v[16:31], v[172:175], v[104:107], v[16:31]
	v_exp_f32_e32 v118, v118
	v_exp_f32_e32 v119, v119
	v_exp_f32_e32 v120, v120
	ds_read_b64_tr_b16 v[104:105], v243 offset:56320
	ds_read_b64_tr_b16 v[106:107], v243 offset:56832
	s_waitcnt lgkmcnt(8)
	v_mfma_f32_32x32x16_bf16 v[32:47], v[160:163], v[214:217], v[32:47]
	v_exp_f32_e32 v121, v121
	v_exp_f32_e32 v122, v122
	v_exp_f32_e32 v123, v123
	ds_read_b128 v[176:179], v244 offset:0
	ds_read_b128 v[180:183], v244 offset:512
	v_mfma_f32_32x32x16_bf16 v[48:63], v[160:163], v[80:83], v[48:63]
	v_exp_f32_e32 v124, v124
	v_exp_f32_e32 v125, v125
	v_exp_f32_e32 v126, v126
	ds_read_b128 v[184:187], v244 offset:2048
	ds_read_b128 v[188:191], v244 offset:2560
	v_mfma_f32_32x32x16_bf16 v[32:47], v[164:167], v[84:87], v[32:47]
	v_exp_f32_e32 v127, v127
	v_exp_f32_e32 v128, v128
	v_exp_f32_e32 v129, v129
	ds_read_b128 v[192:195], v244 offset:4096
	ds_read_b128 v[196:199], v244 offset:4608
	v_mfma_f32_32x32x16_bf16 v[48:63], v[164:167], v[88:91], v[48:63]
	v_exp_f32_e32 v130, v130
	v_exp_f32_e32 v131, v131
	v_exp_f32_e32 v132, v132
	ds_read_b128 v[200:203], v244 offset:6144
	ds_read_b128 v[206:209], v244 offset:6656
	s_waitcnt lgkmcnt(8)
	v_mfma_f32_32x32x16_bf16 v[32:47], v[168:171], v[92:95], v[32:47]
	v_exp_f32_e32 v133, v133
	v_exp_f32_e32 v134, v134
	v_exp_f32_e32 v135, v135
	v_mfma_f32_32x32x16_bf16 v[48:63], v[168:171], v[96:99], v[48:63]
	v_exp_f32_e32 v136, v136
	v_exp_f32_e32 v137, v137
	v_exp_f32_e32 v138, v138
	v_mfma_f32_32x32x16_bf16 v[32:47], v[172:175], v[100:103], v[32:47]
	v_exp_f32_e32 v139, v139
	v_exp_f32_e32 v140, v140
	v_exp_f32_e32 v141, v141
	v_mfma_f32_32x32x16_bf16 v[48:63], v[172:175], v[104:107], v[48:63]
	v_exp_f32_e32 v142, v142
	v_exp_f32_e32 v143, v143
	s_waitcnt vmcnt(3) lgkmcnt(0)
	s_barrier
	s_cbranch_vccnz .Lat_resc_M1

.Lat_step_M2:
	v_add_u32_e32 v243, s16, v204
	ds_read_b64_tr_b16 v[214:215], v243 offset:24576
	ds_read_b64_tr_b16 v[216:217], v243 offset:25088
	v_mfma_f32_32x32x16_bf16 v[80:95], v[176:179], v[144:147], v[64:79]
	v_add_f32_e32 v245, v112, v113
	v_add_f32_e32 v246, v114, v115
	v_add_f32_e32 v245, v116, v245
	v_add_f32_e32 v246, v117, v246
	v_cvt_pk_bf16_f32 v160, v112, v113
	v_cvt_pk_bf16_f32 v161, v114, v115
	ds_read_b64_tr_b16 v[112:113], v243 offset:28672
	ds_read_b64_tr_b16 v[114:115], v243 offset:29184
	v_mfma_f32_32x32x16_bf16 v[96:111], v[180:183], v[144:147], v[64:79]
	v_add_f32_e32 v245, v118, v245
	v_add_f32_e32 v246, v119, v246
	v_add_f32_e32 v245, v120, v245
	v_add_f32_e32 v246, v121, v246
	v_cvt_pk_bf16_f32 v162, v116, v117
	v_cvt_pk_bf16_f32 v163, v118, v119
	ds_read_b64_tr_b16 v[116:117], v243 offset:25600
	ds_read_b64_tr_b16 v[118:119], v243 offset:26112
	v_mfma_f32_32x32x16_bf16 v[80:95], v[184:187], v[148:151], v[80:95]
	v_add_f32_e32 v245, v122, v245
	v_add_f32_e32 v246, v123, v246
	v_add_f32_e32 v245, v124, v245
	v_add_f32_e32 v246, v125, v246
	v_cvt_pk_bf16_f32 v164, v120, v121
	v_cvt_pk_bf16_f32 v165, v122, v123
	ds_read_b64_tr_b16 v[120:121], v243 offset:29696
	ds_read_b64_tr_b16 v[122:123], v243 offset:30208
	v_mfma_f32_32x32x16_bf16 v[96:111], v[188:191], v[148:151], v[96:111]
	v_add_f32_e32 v245, v126, v245
	v_add_f32_e32 v246, v127, v246
	v_add_f32_e32 v245, v128, v245
	v_add_f32_e32 v246, v129, v246
	v_cvt_pk_bf16_f32 v166, v124, v125
	v_cvt_pk_bf16_f32 v167, v126, v127
	ds_read_b64_tr_b16 v[124:125], v243 offset:26624
	ds_read_b64_tr_b16 v[126:127], v243 offset:27136
	v_mfma_f32_32x32x16_bf16 v[80:95], v[192:195], v[152:155], v[80:95]
	v_add_f32_e32 v245, v130, v245
	v_add_f32_e32 v246, v131, v246
	v_add_f32_e32 v245, v132, v245
	v_add_f32_e32 v246, v133, v246
	v_cvt_pk_bf16_f32 v168, v128, v129
	v_cvt_pk_bf16_f32 v169, v130, v131
	ds_read_b64_tr_b16 v[128:129], v243 offset:30720
	ds_read_b64_tr_b16 v[130:131], v243 offset:31232
	v_mfma_f32_32x32x16_bf16 v[96:111], v[196:199], v[152:155], v[96:111]
	v_add_f32_e32 v245, v134, v245
	v_add_f32_e32 v246, v135, v246
	v_add_f32_e32 v245, v136, v245
	v_add_f32_e32 v246, v137, v246
	v_cvt_pk_bf16_f32 v170, v132, v133
	v_cvt_pk_bf16_f32 v171, v134, v135
	ds_read_b64_tr_b16 v[132:133], v243 offset:27648
	ds_read_b64_tr_b16 v[134:135], v243 offset:28160
	v_mfma_f32_32x32x16_bf16 v[80:95], v[200:203], v[156:159], v[80:95]
	v_add_f32_e32 v245, v138, v245
	v_add_f32_e32 v246, v139, v246
	v_add_f32_e32 v245, v140, v245
	v_add_f32_e32 v246, v141, v246
	v_cvt_pk_bf16_f32 v172, v136, v137
	v_cvt_pk_bf16_f32 v173, v138, v139
	ds_read_b64_tr_b16 v[136:137], v243 offset:31744
	ds_read_b64_tr_b16 v[138:139], v243 offset:32256
	v_mfma_f32_32x32x16_bf16 v[96:111], v[206:209], v[156:159], v[96:111]
	v_add_f32_e32 v245, v142, v245
	v_add_f32_e32 v246, v143, v246
	v_add_f32_e32 v245, v245, v246
	v_cvt_pk_bf16_f32 v174, v140, v141
	v_cvt_pk_bf16_f32 v175, v142, v143
	v_add_f32_e32 v211, v211, v245
	v_add_u32_e32 v244, s18, v219
	s_waitcnt lgkmcnt(8)
	v_mfma_f32_32x32x16_bf16 v[0:15], v[160:163], v[214:217], v[0:15]
	v_max3_f32 v246, v80, v81, v82
	v_max3_f32 v247, v83, v84, v85
	ds_read_b64_tr_b16 v[214:215], v243 offset:49152
	ds_read_b64_tr_b16 v[216:217], v243 offset:49664
	v_mfma_f32_32x32x16_bf16 v[16:31], v[160:163], v[112:115], v[16:31]
	s_add_i32 m0, s17, s54
	v_max3_f32 v246, v246, v86, v87
	v_max3_f32 v247, v247, v88, v89
	v_max3_f32 v246, v246, v90, v91
	v_max3_f32 v247, v247, v92, v93
	ds_read_b64_tr_b16 v[112:113], v243 offset:53248
	ds_read_b64_tr_b16 v[114:115], v243 offset:53760
	global_load_lds_dwordx4 v222, s[0:1]
	s_add_u32 s0, s0, 0x20000
	s_addc_u32 s1, s1, 0
	v_mfma_f32_32x32x16_bf16 v[0:15], v[164:167], v[116:119], v[0:15]
	s_add_i32 s21, s18, s54
	s_add_i32 m0, s21, 0x6000
	v_max3_f32 v246, v246, v94, v95
	v_max3_f32 v247, v247, v96, v97
	v_max3_f32 v246, v246, v98, v99
	v_max3_f32 v247, v247, v100, v101
	ds_read_b64_tr_b16 v[116:117], v243 offset:50176
	ds_read_b64_tr_b16 v[118:119], v243 offset:50688
	global_load_lds_dwordx4 v223, s[4:5]
	v_mfma_f32_32x32x16_bf16 v[16:31], v[164:167], v[120:123], v[16:31]
	s_add_i32 m0, s21, 0xc000
	v_max3_f32 v246, v246, v102, v103
	v_max3_f32 v247, v247, v104, v105
	v_max3_f32 v246, v246, v106, v107
	v_max3_f32 v247, v247, v108, v109
	ds_read_b64_tr_b16 v[120:121], v243 offset:54272
	ds_read_b64_tr_b16 v[122:123], v243 offset:54784
	global_load_lds_dwordx4 v224, s[4:5]
	s_add_u32 s4, s4, 0x20000
	s_addc_u32 s5, s5, 0
	s_waitcnt lgkmcnt(8)
	v_mfma_f32_32x32x16_bf16 v[0:15], v[168:171], v[124:127], v[0:15]
	v_max3_f32 v246, v246, v110, v111
	v_max_f32_e32 v248, v246, v247
	ds_read_b64_tr_b16 v[124:125], v243 offset:51200
	ds_read_b64_tr_b16 v[126:127], v243 offset:51712
	v_cmp_lt_f32_e32 vcc, s87, v248
	s_cbranch_vccnz .Lat_rare_M2
.Lat_cont_M2:
	v_mfma_f32_32x32x16_bf16 v[16:31], v[168:171], v[128:131], v[16:31]
	v_exp_f32_e32 v80, v80
	v_exp_f32_e32 v81, v81
	v_exp_f32_e32 v82, v82
	ds_read_b64_tr_b16 v[128:129], v243 offset:55296
	ds_read_b64_tr_b16 v[130:131], v243 offset:55808
	v_mfma_f32_32x32x16_bf16 v[0:15], v[172:175], v[132:135], v[0:15]
	v_exp_f32_e32 v83, v83
	v_exp_f32_e32 v84, v84
	v_exp_f32_e32 v85, v85
	ds_read_b64_tr_b16 v[132:133], v243 offset:52224
	ds_read_b64_tr_b16 v[134:135], v243 offset:52736
	v_mfma_f32_32x32x16_bf16 v[16:31], v[172:175], v[136:139], v[16:31]
	v_exp_f32_e32 v86, v86
	v_exp_f32_e32 v87, v87
	v_exp_f32_e32 v88, v88
	ds_read_b64_tr_b16 v[136:137], v243 offset:56320
	ds_read_b64_tr_b16 v[138:139], v243 offset:56832
	s_waitcnt lgkmcnt(8)
	v_mfma_f32_32x32x16_bf16 v[32:47], v[160:163], v[214:217], v[32:47]
	v_exp_f32_e32 v89, v89
	v_exp_f32_e32 v90, v90
	v_exp_f32_e32 v91, v91
	ds_read_b128 v[176:179], v244 offset:0
	ds_read_b128 v[180:183], v244 offset:512
	v_mfma_f32_32x32x16_bf16 v[48:63], v[160:163], v[112:115], v[48:63]
	v_exp_f32_e32 v92, v92
	v_exp_f32_e32 v93, v93
	v_exp_f32_e32 v94, v94
	ds_read_b128 v[184:187], v244 offset:2048
	ds_read_b128 v[188:191], v244 offset:2560
	v_mfma_f32_32x32x16_bf16 v[32:47], v[164:167], v[116:119], v[32:47]
	v_exp_f32_e32 v95, v95
	v_exp_f32_e32 v96, v96
	v_exp_f32_e32 v97, v97
	ds_read_b128 v[192:195], v244 offset:4096
	ds_read_b128 v[196:199], v244 offset:4608
	v_mfma_f32_32x32x16_bf16 v[48:63], v[164:167], v[120:123], v[48:63]
	v_exp_f32_e32 v98, v98
	v_exp_f32_e32 v99, v99
	v_exp_f32_e32 v100, v100
	ds_read_b128 v[200:203], v244 offset:6144
	ds_read_b128 v[206:209], v244 offset:6656
	s_waitcnt lgkmcnt(8)
	v_mfma_f32_32x32x16_bf16 v[32:47], v[168:171], v[124:127], v[32:47]
	v_exp_f32_e32 v101, v101
	v_exp_f32_e32 v102, v102
	v_exp_f32_e32 v103, v103
	v_mfma_f32_32x32x16_bf16 v[48:63], v[168:171], v[128:131], v[48:63]
	v_exp_f32_e32 v104, v104
	v_exp_f32_e32 v105, v105
	v_exp_f32_e32 v106, v106
	v_mfma_f32_32x32x16_bf16 v[32:47], v[172:175], v[132:135], v[32:47]
	v_exp_f32_e32 v107, v107
	v_exp_f32_e32 v108, v108
	v_exp_f32_e32 v109, v109
	v_mfma_f32_32x32x16_bf16 v[48:63], v[172:175], v[136:139], v[48:63]
	v_exp_f32_e32 v110, v110
	v_exp_f32_e32 v111, v111
	s_waitcnt vmcnt(3) lgkmcnt(0)
	s_barrier
	s_cbranch_vccnz .Lat_resc_M2

.Lat_step_T5:
	v_add_u32_e32 v243, s16, v204
	ds_read_b64_tr_b16 v[214:215], v243 offset:24576
	ds_read_b64_tr_b16 v[216:217], v243 offset:25088
	v_mfma_f32_32x32x16_bf16 v[112:127], v[176:179], v[144:147], v[64:79]
	v_add_f32_e32 v245, v80, v81
	v_add_f32_e32 v246, v82, v83
	v_add_f32_e32 v245, v84, v245
	v_add_f32_e32 v246, v85, v246
	v_cvt_pk_bf16_f32 v160, v80, v81
	v_cvt_pk_bf16_f32 v161, v82, v83
	ds_read_b64_tr_b16 v[80:81], v243 offset:28672
	ds_read_b64_tr_b16 v[82:83], v243 offset:29184
	v_mfma_f32_32x32x16_bf16 v[128:143], v[180:183], v[144:147], v[64:79]
	v_add_f32_e32 v245, v86, v245
	v_add_f32_e32 v246, v87, v246
	v_add_f32_e32 v245, v88, v245
	v_add_f32_e32 v246, v89, v246
	v_cvt_pk_bf16_f32 v162, v84, v85
	v_cvt_pk_bf16_f32 v163, v86, v87
	ds_read_b64_tr_b16 v[84:85], v243 offset:25600
	ds_read_b64_tr_b16 v[86:87], v243 offset:26112
	v_mfma_f32_32x32x16_bf16 v[112:127], v[184:187], v[148:151], v[112:127]
	v_add_f32_e32 v245, v90, v245
	v_add_f32_e32 v246, v91, v246
	v_add_f32_e32 v245, v92, v245
	v_add_f32_e32 v246, v93, v246
	v_cvt_pk_bf16_f32 v164, v88, v89
	v_cvt_pk_bf16_f32 v165, v90, v91
	ds_read_b64_tr_b16 v[88:89], v243 offset:29696
	ds_read_b64_tr_b16 v[90:91], v243 offset:30208
	v_mfma_f32_32x32x16_bf16 v[128:143], v[188:191], v[148:151], v[128:143]
	v_add_f32_e32 v245, v94, v245
	v_add_f32_e32 v246, v95, v246
	v_add_f32_e32 v245, v96, v245
	v_add_f32_e32 v246, v97, v246
	v_cvt_pk_bf16_f32 v166, v92, v93
	v_cvt_pk_bf16_f32 v167, v94, v95
	ds_read_b64_tr_b16 v[92:93], v243 offset:26624
	ds_read_b64_tr_b16 v[94:95], v243 offset:27136
	v_mfma_f32_32x32x16_bf16 v[112:127], v[192:195], v[152:155], v[112:127]
	v_add_f32_e32 v245, v98, v245
	v_add_f32_e32 v246, v99, v246
	v_add_f32_e32 v245, v100, v245
	v_add_f32_e32 v246, v101, v246
	v_cvt_pk_bf16_f32 v168, v96, v97
	v_cvt_pk_bf16_f32 v169, v98, v99
	ds_read_b64_tr_b16 v[96:97], v243 offset:30720
	ds_read_b64_tr_b16 v[98:99], v243 offset:31232
	v_mfma_f32_32x32x16_bf16 v[128:143], v[196:199], v[152:155], v[128:143]
	v_add_f32_e32 v245, v102, v245
	v_add_f32_e32 v246, v103, v246
	v_add_f32_e32 v245, v104, v245
	v_add_f32_e32 v246, v105, v246
	v_cvt_pk_bf16_f32 v170, v100, v101
	v_cvt_pk_bf16_f32 v171, v102, v103
	ds_read_b64_tr_b16 v[100:101], v243 offset:27648
	ds_read_b64_tr_b16 v[102:103], v243 offset:28160
	v_mfma_f32_32x32x16_bf16 v[112:127], v[200:203], v[156:159], v[112:127]
	v_add_f32_e32 v245, v106, v245
	v_add_f32_e32 v246, v107, v246
	v_add_f32_e32 v245, v108, v245
	v_add_f32_e32 v246, v109, v246
	v_cvt_pk_bf16_f32 v172, v104, v105
	v_cvt_pk_bf16_f32 v173, v106, v107
	ds_read_b64_tr_b16 v[104:105], v243 offset:31744
	ds_read_b64_tr_b16 v[106:107], v243 offset:32256
	v_mfma_f32_32x32x16_bf16 v[128:143], v[206:209], v[156:159], v[128:143]
	v_add_f32_e32 v245, v110, v245
	v_add_f32_e32 v246, v111, v246
	v_add_f32_e32 v245, v245, v246
	v_cvt_pk_bf16_f32 v174, v108, v109
	v_cvt_pk_bf16_f32 v175, v110, v111
	v_add_f32_e32 v211, v211, v245
	v_add_u32_e32 v244, s18, v219
	s_waitcnt lgkmcnt(8)
	v_mfma_f32_32x32x16_bf16 v[0:15], v[160:163], v[214:217], v[0:15]
	v_max3_f32 v246, v112, v113, v114
	v_max3_f32 v247, v115, v116, v117
	ds_read_b64_tr_b16 v[214:215], v243 offset:49152
	ds_read_b64_tr_b16 v[216:217], v243 offset:49664
	v_mfma_f32_32x32x16_bf16 v[16:31], v[160:163], v[80:83], v[16:31]
	s_add_i32 m0, s17, s54
	v_max3_f32 v246, v246, v118, v119
	v_max3_f32 v247, v247, v120, v121
	v_max3_f32 v246, v246, v122, v123
	v_max3_f32 v247, v247, v124, v125
	ds_read_b64_tr_b16 v[80:81], v243 offset:53248
	ds_read_b64_tr_b16 v[82:83], v243 offset:53760
	global_load_lds_dwordx4 v222, s[0:1]
	s_add_u32 s0, s0, 0x20000
	s_addc_u32 s1, s1, 0
	v_mfma_f32_32x32x16_bf16 v[0:15], v[164:167], v[84:87], v[0:15]
	s_add_i32 s21, s18, s54
	s_add_i32 m0, s21, 0x6000
	v_max3_f32 v246, v246, v126, v127
	v_max3_f32 v247, v247, v128, v129
	v_max3_f32 v246, v246, v130, v131
	v_max3_f32 v247, v247, v132, v133
	ds_read_b64_tr_b16 v[84:85], v243 offset:50176
	ds_read_b64_tr_b16 v[86:87], v243 offset:50688
	global_load_lds_dwordx4 v223, s[4:5]
	v_mfma_f32_32x32x16_bf16 v[16:31], v[164:167], v[88:91], v[16:31]
	s_add_i32 m0, s21, 0xc000
	v_max3_f32 v246, v246, v134, v135
	v_max3_f32 v247, v247, v136, v137
	v_max3_f32 v246, v246, v138, v139
	v_max3_f32 v247, v247, v140, v141
	ds_read_b64_tr_b16 v[88:89], v243 offset:54272
	ds_read_b64_tr_b16 v[90:91], v243 offset:54784
	global_load_lds_dwordx4 v224, s[4:5]
	s_add_u32 s4, s4, 0x20000
	s_addc_u32 s5, s5, 0
	s_waitcnt lgkmcnt(8)
	v_mfma_f32_32x32x16_bf16 v[0:15], v[168:171], v[92:95], v[0:15]
	v_max3_f32 v246, v246, v142, v143
	v_max_f32_e32 v248, v246, v247
	ds_read_b64_tr_b16 v[92:93], v243 offset:51200
	ds_read_b64_tr_b16 v[94:95], v243 offset:51712
	v_cmp_lt_f32_e32 vcc, s87, v248
	s_cbranch_vccnz .Lat_rare_T5

; __device__ __forceinline__ void cmask(f32x16&p0,f32x16&p1,int jb,int qrel,int hi){
;   const float NEG=-INFINITY; int kb=64*jb+4*hi;
;   #pragma unroll
;   for(int r=0;r<16;++r){int kv=kb+(r&3)+8*(r>>2); if(kv>qrel)p0[r]=NEG; if(kv+32>qrel)p1[r]=NEG;}
; }
.Lat_step_T4:
	v_add_u32_e32 v243, s16, v204
	ds_read_b64_tr_b16 v[214:215], v243 offset:24576
	ds_read_b64_tr_b16 v[216:217], v243 offset:25088
	v_mfma_f32_32x32x16_bf16 v[80:95], v[176:179], v[144:147], v[64:79]
	v_add_f32_e32 v245, v112, v113
	v_add_f32_e32 v246, v114, v115
	v_add_f32_e32 v245, v116, v245
	v_add_f32_e32 v246, v117, v246
	v_cvt_pk_bf16_f32 v160, v112, v113
	v_cvt_pk_bf16_f32 v161, v114, v115
	ds_read_b64_tr_b16 v[112:113], v243 offset:28672
	ds_read_b64_tr_b16 v[114:115], v243 offset:29184
	v_mfma_f32_32x32x16_bf16 v[96:111], v[180:183], v[144:147], v[64:79]
	v_add_f32_e32 v245, v118, v245
	v_add_f32_e32 v246, v119, v246
	v_add_f32_e32 v245, v120, v245
	v_add_f32_e32 v246, v121, v246
	v_cvt_pk_bf16_f32 v162, v116, v117
	v_cvt_pk_bf16_f32 v163, v118, v119
	ds_read_b64_tr_b16 v[116:117], v243 offset:25600
	ds_read_b64_tr_b16 v[118:119], v243 offset:26112
	v_mfma_f32_32x32x16_bf16 v[80:95], v[184:187], v[148:151], v[80:95]
	v_add_f32_e32 v245, v122, v245
	v_add_f32_e32 v246, v123, v246
	v_add_f32_e32 v245, v124, v245
	v_add_f32_e32 v246, v125, v246
	v_cvt_pk_bf16_f32 v164, v120, v121
	v_cvt_pk_bf16_f32 v165, v122, v123
	ds_read_b64_tr_b16 v[120:121], v243 offset:29696
	ds_read_b64_tr_b16 v[122:123], v243 offset:30208
	v_mfma_f32_32x32x16_bf16 v[96:111], v[188:191], v[148:151], v[96:111]
	v_add_f32_e32 v245, v126, v245
	v_add_f32_e32 v246, v127, v246
	v_add_f32_e32 v245, v128, v245
	v_add_f32_e32 v246, v129, v246
	v_cvt_pk_bf16_f32 v166, v124, v125
	v_cvt_pk_bf16_f32 v167, v126, v127
	ds_read_b64_tr_b16 v[124:125], v243 offset:26624
	ds_read_b64_tr_b16 v[126:127], v243 offset:27136
	v_mfma_f32_32x32x16_bf16 v[80:95], v[192:195], v[152:155], v[80:95]
	v_add_f32_e32 v245, v130, v245
	v_add_f32_e32 v246, v131, v246
	v_add_f32_e32 v245, v132, v245
	v_add_f32_e32 v246, v133, v246
	v_cvt_pk_bf16_f32 v168, v128, v129
	v_cvt_pk_bf16_f32 v169, v130, v131
	ds_read_b64_tr_b16 v[128:129], v243 offset:30720
	ds_read_b64_tr_b16 v[130:131], v243 offset:31232
	v_mfma_f32_32x32x16_bf16 v[96:111], v[196:199], v[152:155], v[96:111]
	v_add_f32_e32 v245, v134, v245
	v_add_f32_e32 v246, v135, v246
	v_add_f32_e32 v245, v136, v245
	v_add_f32_e32 v246, v137, v246
	v_cvt_pk_bf16_f32 v170, v132, v133
	v_cvt_pk_bf16_f32 v171, v134, v135
	ds_read_b64_tr_b16 v[132:133], v243 offset:27648
	ds_read_b64_tr_b16 v[134:135], v243 offset:28160
	v_mfma_f32_32x32x16_bf16 v[80:95], v[200:203], v[156:159], v[80:95]
	v_add_f32_e32 v245, v138, v245
	v_add_f32_e32 v246, v139, v246
	v_add_f32_e32 v245, v140, v245
	v_add_f32_e32 v246, v141, v246
	v_cvt_pk_bf16_f32 v172, v136, v137
	v_cvt_pk_bf16_f32 v173, v138, v139
	ds_read_b64_tr_b16 v[136:137], v243 offset:31744
	ds_read_b64_tr_b16 v[138:139], v243 offset:32256
	v_mfma_f32_32x32x16_bf16 v[96:111], v[206:209], v[156:159], v[96:111]
	v_add_f32_e32 v245, v142, v245
	v_add_f32_e32 v246, v143, v246
	v_add_f32_e32 v245, v245, v246
	v_cvt_pk_bf16_f32 v174, v140, v141
	v_cvt_pk_bf16_f32 v175, v142, v143
	v_add_f32_e32 v211, v211, v245
	v_add_u32_e32 v244, s18, v219
	s_waitcnt lgkmcnt(8)
	v_mfma_f32_32x32x16_bf16 v[0:15], v[160:163], v[214:217], v[0:15]
	v_cmp_gt_i32_e64 s[28:29], 0, v225
	v_cmp_gt_i32_e64 s[30:31], 1, v225
	v_cmp_gt_i32_e64 s[34:35], 2, v225
	v_cndmask_b32_e64 v80, v80, v241, s[28:29]
	v_cmp_gt_i32_e64 s[28:29], 3, v225
	v_cndmask_b32_e64 v81, v81, v241, s[30:31]
	v_cmp_gt_i32_e64 s[30:31], 8, v225
	v_cndmask_b32_e64 v82, v82, v241, s[34:35]
	v_cmp_gt_i32_e64 s[34:35], 9, v225
	v_cndmask_b32_e64 v83, v83, v241, s[28:29]
	ds_read_b64_tr_b16 v[214:215], v243 offset:49152
	ds_read_b64_tr_b16 v[216:217], v243 offset:49664
	v_mfma_f32_32x32x16_bf16 v[16:31], v[160:163], v[112:115], v[16:31]
	s_add_i32 m0, s17, s54
	v_cmp_gt_i32_e64 s[28:29], 10, v225
	v_cndmask_b32_e64 v84, v84, v241, s[30:31]
	v_cmp_gt_i32_e64 s[30:31], 11, v225
	v_cndmask_b32_e64 v85, v85, v241, s[34:35]
	v_cmp_gt_i32_e64 s[34:35], 16, v225
	v_cndmask_b32_e64 v86, v86, v241, s[28:29]
	v_cmp_gt_i32_e64 s[28:29], 17, v225
	v_cndmask_b32_e64 v87, v87, v241, s[30:31]
	v_cmp_gt_i32_e64 s[30:31], 18, v225
	v_cndmask_b32_e64 v88, v88, v241, s[34:35]
	ds_read_b64_tr_b16 v[112:113], v243 offset:53248
	ds_read_b64_tr_b16 v[114:115], v243 offset:53760
	global_load_lds_dwordx4 v222, s[0:1]
	s_add_u32 s0, s0, 0x20000
	s_addc_u32 s1, s1, 0
	v_mfma_f32_32x32x16_bf16 v[0:15], v[164:167], v[116:119], v[0:15]
	s_add_i32 s21, s18, s54
	s_add_i32 m0, s21, 0x6000
	v_cmp_gt_i32_e64 s[34:35], 19, v225
	v_cndmask_b32_e64 v89, v89, v241, s[28:29]
	v_cmp_gt_i32_e64 s[28:29], 24, v225
	v_cndmask_b32_e64 v90, v90, v241, s[30:31]
	v_cmp_gt_i32_e64 s[30:31], 25, v225
	v_cndmask_b32_e64 v91, v91, v241, s[34:35]
	v_cmp_gt_i32_e64 s[34:35], 26, v225
	v_cndmask_b32_e64 v92, v92, v241, s[28:29]
	v_cmp_gt_i32_e64 s[28:29], 27, v225
	v_cndmask_b32_e64 v93, v93, v241, s[30:31]
	ds_read_b64_tr_b16 v[116:117], v243 offset:50176
	ds_read_b64_tr_b16 v[118:119], v243 offset:50688
	global_load_lds_dwordx4 v223, s[4:5]
	v_mfma_f32_32x32x16_bf16 v[16:31], v[164:167], v[120:123], v[16:31]
	s_add_i32 m0, s21, 0xc000
	v_cmp_gt_i32_e64 s[30:31], 32, v225
	v_cndmask_b32_e64 v94, v94, v241, s[34:35]
	v_cmp_gt_i32_e64 s[34:35], 33, v225
	v_cndmask_b32_e64 v95, v95, v241, s[28:29]
	v_cmp_gt_i32_e64 s[28:29], 34, v225
	v_cndmask_b32_e64 v96, v96, v241, s[30:31]
	v_cmp_gt_i32_e64 s[30:31], 35, v225
	v_cndmask_b32_e64 v97, v97, v241, s[34:35]
	v_cmp_gt_i32_e64 s[34:35], 40, v225
	v_cndmask_b32_e64 v98, v98, v241, s[28:29]
	ds_read_b64_tr_b16 v[120:121], v243 offset:54272
	ds_read_b64_tr_b16 v[122:123], v243 offset:54784
	global_load_lds_dwordx4 v224, s[4:5]
	s_add_u32 s4, s4, 0x20000
	s_addc_u32 s5, s5, 0
	s_waitcnt lgkmcnt(8)
; __device__ __forceinline__ void cmask(f32x16&p0,f32x16&p1,int jb,int qrel,int hi){
;   const float NEG=-INFINITY; int kb=64*jb+4*hi;
;   #pragma unroll
;   for(int r=0;r<16;++r){int kv=kb+(r&3)+8*(r>>2); if(kv>qrel)p0[r]=NEG; if(kv+32>qrel)p1[r]=NEG;}
; }
	v_mfma_f32_32x32x16_bf16 v[0:15], v[168:171], v[124:127], v[0:15]
	v_cmp_gt_i32_e64 s[28:29], 41, v225
	v_cndmask_b32_e64 v99, v99, v241, s[30:31]
	v_cmp_gt_i32_e64 s[30:31], 42, v225
	v_cndmask_b32_e64 v100, v100, v241, s[34:35]
	v_cmp_gt_i32_e64 s[34:35], 43, v225
	v_cndmask_b32_e64 v101, v101, v241, s[28:29]
	v_cmp_gt_i32_e64 s[28:29], 48, v225
	v_cndmask_b32_e64 v102, v102, v241, s[30:31]
	v_cmp_gt_i32_e64 s[30:31], 49, v225
	v_cndmask_b32_e64 v103, v103, v241, s[34:35]
	ds_read_b64_tr_b16 v[124:125], v243 offset:51200
	ds_read_b64_tr_b16 v[126:127], v243 offset:51712
	v_mfma_f32_32x32x16_bf16 v[16:31], v[168:171], v[128:131], v[16:31]
	v_cmp_gt_i32_e64 s[34:35], 50, v225
	v_cndmask_b32_e64 v104, v104, v241, s[28:29]
	v_cmp_gt_i32_e64 s[28:29], 51, v225
	v_cndmask_b32_e64 v105, v105, v241, s[30:31]
	v_cmp_gt_i32_e64 s[30:31], 56, v225
	v_cndmask_b32_e64 v106, v106, v241, s[34:35]
	v_cmp_gt_i32_e64 s[34:35], 57, v225
	v_cndmask_b32_e64 v107, v107, v241, s[28:29]
	v_cmp_gt_i32_e64 s[28:29], 58, v225
	v_cndmask_b32_e64 v108, v108, v241, s[30:31]
	ds_read_b64_tr_b16 v[128:129], v243 offset:55296
	ds_read_b64_tr_b16 v[130:131], v243 offset:55808
	v_mfma_f32_32x32x16_bf16 v[0:15], v[172:175], v[132:135], v[0:15]
	v_cmp_gt_i32_e64 s[30:31], 59, v225
	v_cndmask_b32_e64 v109, v109, v241, s[34:35]
	v_cndmask_b32_e64 v110, v110, v241, s[28:29]
	v_cndmask_b32_e64 v111, v111, v241, s[30:31]
	v_max3_f32 v246, v80, v81, v82
	v_max3_f32 v247, v83, v84, v85
	v_max3_f32 v246, v246, v86, v87
	v_max3_f32 v247, v247, v88, v89
	v_max3_f32 v246, v246, v90, v91
	v_max3_f32 v247, v247, v92, v93
	ds_read_b64_tr_b16 v[132:133], v243 offset:52224
	ds_read_b64_tr_b16 v[134:135], v243 offset:52736
	v_mfma_f32_32x32x16_bf16 v[16:31], v[172:175], v[136:139], v[16:31]
	v_max3_f32 v246, v246, v94, v95
	v_max3_f32 v247, v247, v96, v97
	v_max3_f32 v246, v246, v98, v99
	v_max3_f32 v247, v247, v100, v101
	v_max3_f32 v246, v246, v102, v103
	v_max3_f32 v247, v247, v104, v105
	v_max3_f32 v246, v246, v106, v107
	v_max3_f32 v247, v247, v108, v109
	v_max3_f32 v246, v246, v110, v111
	v_max_f32_e32 v248, v246, v247
	ds_read_b64_tr_b16 v[136:137], v243 offset:56320
	ds_read_b64_tr_b16 v[138:139], v243 offset:56832
	s_waitcnt lgkmcnt(8)
	v_mfma_f32_32x32x16_bf16 v[32:47], v[160:163], v[214:217], v[32:47]
	ds_read_b128 v[176:179], v244 offset:0
	ds_read_b128 v[180:183], v244 offset:512
	v_cmp_lt_f32_e32 vcc, s87, v248
	s_cbranch_vccnz .Lat_rare_T4
.Lat_cont_T4:
	v_mfma_f32_32x32x16_bf16 v[48:63], v[160:163], v[112:115], v[48:63]
	v_exp_f32_e32 v80, v80
	v_exp_f32_e32 v81, v81
	v_exp_f32_e32 v82, v82
	v_exp_f32_e32 v83, v83
	v_exp_f32_e32 v84, v84
	ds_read_b128 v[184:187], v244 offset:2048
	ds_read_b128 v[188:191], v244 offset:2560
	v_mfma_f32_32x32x16_bf16 v[32:47], v[164:167], v[116:119], v[32:47]
	v_exp_f32_e32 v85, v85
	v_exp_f32_e32 v86, v86
	v_exp_f32_e32 v87, v87
	v_exp_f32_e32 v88, v88
	v_exp_f32_e32 v89, v89
	ds_read_b128 v[192:195], v244 offset:4096
	ds_read_b128 v[196:199], v244 offset:4608
	v_mfma_f32_32x32x16_bf16 v[48:63], v[164:167], v[120:123], v[48:63]
	v_exp_f32_e32 v90, v90
	v_exp_f32_e32 v91, v91
	v_exp_f32_e32 v92, v92
	v_exp_f32_e32 v93, v93
	v_exp_f32_e32 v94, v94
	ds_read_b128 v[200:203], v244 offset:6144
	ds_read_b128 v[206:209], v244 offset:6656
	s_waitcnt lgkmcnt(8)
	v_mfma_f32_32x32x16_bf16 v[32:47], v[168:171], v[124:127], v[32:47]
	v_exp_f32_e32 v95, v95
	v_exp_f32_e32 v96, v96
	v_exp_f32_e32 v97, v97
	v_exp_f32_e32 v98, v98
	v_exp_f32_e32 v99, v99
	v_mfma_f32_32x32x16_bf16 v[48:63], v[168:171], v[128:131], v[48:63]
	v_exp_f32_e32 v100, v100
	v_exp_f32_e32 v101, v101
	v_exp_f32_e32 v102, v102
	v_exp_f32_e32 v103, v103
	v_mfma_f32_32x32x16_bf16 v[32:47], v[172:175], v[132:135], v[32:47]
	v_exp_f32_e32 v104, v104
	v_exp_f32_e32 v105, v105
	v_exp_f32_e32 v106, v106
	v_exp_f32_e32 v107, v107
	v_mfma_f32_32x32x16_bf16 v[48:63], v[172:175], v[136:139], v[48:63]
	v_exp_f32_e32 v108, v108
	v_exp_f32_e32 v109, v109
	v_exp_f32_e32 v110, v110
	v_exp_f32_e32 v111, v111
	s_waitcnt vmcnt(3) lgkmcnt(0)
	s_barrier
	s_cbranch_vccnz .Lat_resc_T4

; __device__ __forceinline__ void cmask(f32x16&p0,f32x16&p1,int jb,int qrel,int hi){
;   const float NEG=-INFINITY; int kb=64*jb+4*hi;
;   #pragma unroll
;   for(int r=0;r<16;++r){int kv=kb+(r&3)+8*(r>>2); if(kv>qrel)p0[r]=NEG; if(kv+32>qrel)p1[r]=NEG;}
; }
.Lat_step_T3:
	s_cmp_lt_u32 s55, 1
	s_cbranch_scc1 .Lat_T3_light
	v_add_u32_e32 v243, s16, v204
	ds_read_b64_tr_b16 v[214:215], v243 offset:24576
	ds_read_b64_tr_b16 v[216:217], v243 offset:25088
	v_mfma_f32_32x32x16_bf16 v[112:127], v[176:179], v[144:147], v[64:79]
	v_add_f32_e32 v245, v80, v81
	v_add_f32_e32 v246, v82, v83
	v_add_f32_e32 v245, v84, v245
	v_add_f32_e32 v246, v85, v246
	v_cvt_pk_bf16_f32 v160, v80, v81
	v_cvt_pk_bf16_f32 v161, v82, v83
	ds_read_b64_tr_b16 v[80:81], v243 offset:28672
	ds_read_b64_tr_b16 v[82:83], v243 offset:29184
	v_mfma_f32_32x32x16_bf16 v[128:143], v[180:183], v[144:147], v[64:79]
	v_add_f32_e32 v245, v86, v245
	v_add_f32_e32 v246, v87, v246
	v_add_f32_e32 v245, v88, v245
	v_add_f32_e32 v246, v89, v246
	v_cvt_pk_bf16_f32 v162, v84, v85
	v_cvt_pk_bf16_f32 v163, v86, v87
	ds_read_b64_tr_b16 v[84:85], v243 offset:25600
	ds_read_b64_tr_b16 v[86:87], v243 offset:26112
	v_mfma_f32_32x32x16_bf16 v[112:127], v[184:187], v[148:151], v[112:127]
	v_add_f32_e32 v245, v90, v245
	v_add_f32_e32 v246, v91, v246
	v_add_f32_e32 v245, v92, v245
	v_add_f32_e32 v246, v93, v246
	v_cvt_pk_bf16_f32 v164, v88, v89
	v_cvt_pk_bf16_f32 v165, v90, v91
	ds_read_b64_tr_b16 v[88:89], v243 offset:29696
	ds_read_b64_tr_b16 v[90:91], v243 offset:30208
	v_mfma_f32_32x32x16_bf16 v[128:143], v[188:191], v[148:151], v[128:143]
	v_add_f32_e32 v245, v94, v245
	v_add_f32_e32 v246, v95, v246
	v_add_f32_e32 v245, v96, v245
	v_add_f32_e32 v246, v97, v246
	v_cvt_pk_bf16_f32 v166, v92, v93
	v_cvt_pk_bf16_f32 v167, v94, v95
	ds_read_b64_tr_b16 v[92:93], v243 offset:26624
	ds_read_b64_tr_b16 v[94:95], v243 offset:27136
	v_mfma_f32_32x32x16_bf16 v[112:127], v[192:195], v[152:155], v[112:127]
	v_add_f32_e32 v245, v98, v245
	v_add_f32_e32 v246, v99, v246
	v_add_f32_e32 v245, v100, v245
	v_add_f32_e32 v246, v101, v246
	v_cvt_pk_bf16_f32 v168, v96, v97
	v_cvt_pk_bf16_f32 v169, v98, v99
	ds_read_b64_tr_b16 v[96:97], v243 offset:30720
	ds_read_b64_tr_b16 v[98:99], v243 offset:31232
	v_mfma_f32_32x32x16_bf16 v[128:143], v[196:199], v[152:155], v[128:143]
	v_add_f32_e32 v245, v102, v245
	v_add_f32_e32 v246, v103, v246
	v_add_f32_e32 v245, v104, v245
	v_add_f32_e32 v246, v105, v246
	v_cvt_pk_bf16_f32 v170, v100, v101
	v_cvt_pk_bf16_f32 v171, v102, v103
	ds_read_b64_tr_b16 v[100:101], v243 offset:27648
	ds_read_b64_tr_b16 v[102:103], v243 offset:28160
	v_mfma_f32_32x32x16_bf16 v[112:127], v[200:203], v[156:159], v[112:127]
	v_add_f32_e32 v245, v106, v245
	v_add_f32_e32 v246, v107, v246
	v_add_f32_e32 v245, v108, v245
	v_add_f32_e32 v246, v109, v246
	v_cvt_pk_bf16_f32 v172, v104, v105
	v_cvt_pk_bf16_f32 v173, v106, v107
	ds_read_b64_tr_b16 v[104:105], v243 offset:31744
	ds_read_b64_tr_b16 v[106:107], v243 offset:32256
	v_mfma_f32_32x32x16_bf16 v[128:143], v[206:209], v[156:159], v[128:143]
	v_add_f32_e32 v245, v110, v245
	v_add_f32_e32 v246, v111, v246
	v_add_f32_e32 v245, v245, v246
	v_cvt_pk_bf16_f32 v174, v108, v109
	v_cvt_pk_bf16_f32 v175, v110, v111
	v_add_f32_e32 v211, v211, v245
	v_add_u32_e32 v244, s18, v219
	s_waitcnt lgkmcnt(8)
	v_mfma_f32_32x32x16_bf16 v[0:15], v[160:163], v[214:217], v[0:15]
	v_add_u32_e32 v242, 0xffffffc0, v225
	v_cmp_gt_i32_e64 s[28:29], 0, v242
	v_cmp_gt_i32_e64 s[30:31], 1, v242
	v_cmp_gt_i32_e64 s[34:35], 2, v242
	v_cndmask_b32_e64 v112, v112, v241, s[28:29]
	v_cmp_gt_i32_e64 s[28:29], 3, v242
	v_cndmask_b32_e64 v113, v113, v241, s[30:31]
	v_cmp_gt_i32_e64 s[30:31], 8, v242
	v_cndmask_b32_e64 v114, v114, v241, s[34:35]
	v_cmp_gt_i32_e64 s[34:35], 9, v242
	ds_read_b64_tr_b16 v[214:215], v243 offset:49152
	ds_read_b64_tr_b16 v[216:217], v243 offset:49664
	v_mfma_f32_32x32x16_bf16 v[16:31], v[160:163], v[80:83], v[16:31]
	v_cndmask_b32_e64 v115, v115, v241, s[28:29]
	v_cmp_gt_i32_e64 s[28:29], 10, v242
	v_cndmask_b32_e64 v116, v116, v241, s[30:31]
	v_cmp_gt_i32_e64 s[30:31], 11, v242
	v_cndmask_b32_e64 v117, v117, v241, s[34:35]
	v_cmp_gt_i32_e64 s[34:35], 16, v242
	v_cndmask_b32_e64 v118, v118, v241, s[28:29]
	v_cmp_gt_i32_e64 s[28:29], 17, v242
	v_cndmask_b32_e64 v119, v119, v241, s[30:31]
	v_cmp_gt_i32_e64 s[30:31], 18, v242
	ds_read_b64_tr_b16 v[80:81], v243 offset:53248
	ds_read_b64_tr_b16 v[82:83], v243 offset:53760
	v_mfma_f32_32x32x16_bf16 v[0:15], v[164:167], v[84:87], v[0:15]
	s_add_i32 s21, s18, s54
	s_add_i32 m0, s21, 0x6000
	v_cndmask_b32_e64 v120, v120, v241, s[34:35]
	v_cmp_gt_i32_e64 s[34:35], 19, v242
	v_cndmask_b32_e64 v121, v121, v241, s[28:29]
	v_cmp_gt_i32_e64 s[28:29], 24, v242
	v_cndmask_b32_e64 v122, v122, v241, s[30:31]
	v_cmp_gt_i32_e64 s[30:31], 25, v242
	v_cndmask_b32_e64 v123, v123, v241, s[34:35]
	v_cmp_gt_i32_e64 s[34:35], 26, v242
	v_cndmask_b32_e64 v124, v124, v241, s[28:29]
	v_cmp_gt_i32_e64 s[28:29], 27, v242
	ds_read_b64_tr_b16 v[84:85], v243 offset:50176
	ds_read_b64_tr_b16 v[86:87], v243 offset:50688
	global_load_lds_dwordx4 v223, s[4:5]
	v_mfma_f32_32x32x16_bf16 v[16:31], v[164:167], v[88:91], v[16:31]
	s_add_i32 m0, s21, 0xc000
	v_cndmask_b32_e64 v125, v125, v241, s[30:31]
	v_cmp_gt_i32_e64 s[30:31], 32, v242
	v_cndmask_b32_e64 v126, v126, v241, s[34:35]
	v_cmp_gt_i32_e64 s[34:35], 33, v242
	v_cndmask_b32_e64 v127, v127, v241, s[28:29]
	v_cmp_gt_i32_e64 s[28:29], 34, v242
	v_cndmask_b32_e64 v128, v128, v241, s[30:31]
	v_cmp_gt_i32_e64 s[30:31], 35, v242
	v_cndmask_b32_e64 v129, v129, v241, s[34:35]
	v_cmp_gt_i32_e64 s[34:35], 40, v242
	ds_read_b64_tr_b16 v[88:89], v243 offset:54272
	ds_read_b64_tr_b16 v[90:91], v243 offset:54784
	global_load_lds_dwordx4 v224, s[4:5]
	s_add_u32 s4, s4, 0x20000
	s_addc_u32 s5, s5, 0
	s_waitcnt lgkmcnt(8)
; __device__ __forceinline__ void cmask(f32x16&p0,f32x16&p1,int jb,int qrel,int hi){
;   const float NEG=-INFINITY; int kb=64*jb+4*hi;
;   #pragma unroll
;   for(int r=0;r<16;++r){int kv=kb+(r&3)+8*(r>>2); if(kv>qrel)p0[r]=NEG; if(kv+32>qrel)p1[r]=NEG;}
; }
	v_mfma_f32_32x32x16_bf16 v[0:15], v[168:171], v[92:95], v[0:15]
	v_cndmask_b32_e64 v130, v130, v241, s[28:29]
	v_cmp_gt_i32_e64 s[28:29], 41, v242
	v_cndmask_b32_e64 v131, v131, v241, s[30:31]
	v_cmp_gt_i32_e64 s[30:31], 42, v242
	v_cndmask_b32_e64 v132, v132, v241, s[34:35]
	v_cmp_gt_i32_e64 s[34:35], 43, v242
	v_cndmask_b32_e64 v133, v133, v241, s[28:29]
	v_cmp_gt_i32_e64 s[28:29], 48, v242
	v_cndmask_b32_e64 v134, v134, v241, s[30:31]
	v_cmp_gt_i32_e64 s[30:31], 49, v242
	ds_read_b64_tr_b16 v[92:93], v243 offset:51200
	ds_read_b64_tr_b16 v[94:95], v243 offset:51712
	v_mfma_f32_32x32x16_bf16 v[16:31], v[168:171], v[96:99], v[16:31]
	v_cndmask_b32_e64 v135, v135, v241, s[34:35]
	v_cmp_gt_i32_e64 s[34:35], 50, v242
	v_cndmask_b32_e64 v136, v136, v241, s[28:29]
	v_cmp_gt_i32_e64 s[28:29], 51, v242
	v_cndmask_b32_e64 v137, v137, v241, s[30:31]
	v_cmp_gt_i32_e64 s[30:31], 56, v242
	v_cndmask_b32_e64 v138, v138, v241, s[34:35]
	v_cmp_gt_i32_e64 s[34:35], 57, v242
	v_cndmask_b32_e64 v139, v139, v241, s[28:29]
	v_cmp_gt_i32_e64 s[28:29], 58, v242
	ds_read_b64_tr_b16 v[96:97], v243 offset:55296
	ds_read_b64_tr_b16 v[98:99], v243 offset:55808
	v_mfma_f32_32x32x16_bf16 v[0:15], v[172:175], v[100:103], v[0:15]
	v_cndmask_b32_e64 v140, v140, v241, s[30:31]
	v_cmp_gt_i32_e64 s[30:31], 59, v242
	v_cndmask_b32_e64 v141, v141, v241, s[34:35]
	v_cndmask_b32_e64 v142, v142, v241, s[28:29]
	v_cndmask_b32_e64 v143, v143, v241, s[30:31]
	v_max3_f32 v246, v112, v113, v114
	v_max3_f32 v247, v115, v116, v117
	v_max3_f32 v246, v246, v118, v119
	v_max3_f32 v247, v247, v120, v121
	v_max3_f32 v246, v246, v122, v123
	ds_read_b64_tr_b16 v[100:101], v243 offset:52224
	ds_read_b64_tr_b16 v[102:103], v243 offset:52736
	v_mfma_f32_32x32x16_bf16 v[16:31], v[172:175], v[104:107], v[16:31]
	v_max3_f32 v247, v247, v124, v125
	v_max3_f32 v246, v246, v126, v127
	v_max3_f32 v247, v247, v128, v129
	v_max3_f32 v246, v246, v130, v131
	v_max3_f32 v247, v247, v132, v133
	v_max3_f32 v246, v246, v134, v135
	v_max3_f32 v247, v247, v136, v137
	v_max3_f32 v246, v246, v138, v139
	v_max3_f32 v247, v247, v140, v141
	v_max3_f32 v246, v246, v142, v143
	ds_read_b64_tr_b16 v[104:105], v243 offset:56320
	ds_read_b64_tr_b16 v[106:107], v243 offset:56832
	s_waitcnt lgkmcnt(8)
	v_mfma_f32_32x32x16_bf16 v[32:47], v[160:163], v[214:217], v[32:47]
	v_max_f32_e32 v248, v246, v247
	ds_read_b128 v[176:179], v244 offset:0
	ds_read_b128 v[180:183], v244 offset:512
	v_cmp_lt_f32_e32 vcc, s87, v248
	s_cbranch_vccnz .Lat_rare_T3
.Lat_cont_T3:
	v_mfma_f32_32x32x16_bf16 v[48:63], v[160:163], v[80:83], v[48:63]
	v_exp_f32_e32 v112, v112
	v_exp_f32_e32 v113, v113
	v_exp_f32_e32 v114, v114
	v_exp_f32_e32 v115, v115
	v_exp_f32_e32 v116, v116
	ds_read_b128 v[184:187], v244 offset:2048
	ds_read_b128 v[188:191], v244 offset:2560
	v_mfma_f32_32x32x16_bf16 v[32:47], v[164:167], v[84:87], v[32:47]
	v_exp_f32_e32 v117, v117
	v_exp_f32_e32 v118, v118
	v_exp_f32_e32 v119, v119
	v_exp_f32_e32 v120, v120
	v_exp_f32_e32 v121, v121
	ds_read_b128 v[192:195], v244 offset:4096
	ds_read_b128 v[196:199], v244 offset:4608
	v_mfma_f32_32x32x16_bf16 v[48:63], v[164:167], v[88:91], v[48:63]
	v_exp_f32_e32 v122, v122
	v_exp_f32_e32 v123, v123
	v_exp_f32_e32 v124, v124
	v_exp_f32_e32 v125, v125
	v_exp_f32_e32 v126, v126
	ds_read_b128 v[200:203], v244 offset:6144
	ds_read_b128 v[206:209], v244 offset:6656
	s_waitcnt lgkmcnt(8)
	v_mfma_f32_32x32x16_bf16 v[32:47], v[168:171], v[92:95], v[32:47]
	v_exp_f32_e32 v127, v127
	v_exp_f32_e32 v128, v128
	v_exp_f32_e32 v129, v129
	v_exp_f32_e32 v130, v130
	v_exp_f32_e32 v131, v131
	v_mfma_f32_32x32x16_bf16 v[48:63], v[168:171], v[96:99], v[48:63]
	v_exp_f32_e32 v132, v132
	v_exp_f32_e32 v133, v133
	v_exp_f32_e32 v134, v134
	v_exp_f32_e32 v135, v135
	v_mfma_f32_32x32x16_bf16 v[32:47], v[172:175], v[100:103], v[32:47]
	v_exp_f32_e32 v136, v136
	v_exp_f32_e32 v137, v137
	v_exp_f32_e32 v138, v138
	v_exp_f32_e32 v139, v139
	v_mfma_f32_32x32x16_bf16 v[48:63], v[172:175], v[104:107], v[48:63]
	v_exp_f32_e32 v140, v140
	v_exp_f32_e32 v141, v141
	v_exp_f32_e32 v142, v142
	v_exp_f32_e32 v143, v143
	s_waitcnt vmcnt(2) lgkmcnt(0)
	s_barrier
	s_cbranch_vccnz .Lat_resc_T3

.Lat_T3_light:
	s_cmp_lt_u32 s55, 0
	s_cbranch_scc1 .Lat_T3_empty
	v_add_u32_e32 v243, s16, v204
	ds_read_b64_tr_b16 v[214:215], v243 offset:24576
	ds_read_b64_tr_b16 v[216:217], v243 offset:25088
	v_add_f32_e32 v245, v80, v81
	v_add_f32_e32 v246, v82, v83
	v_add_f32_e32 v245, v84, v245
	v_add_f32_e32 v246, v85, v246
	v_cvt_pk_bf16_f32 v160, v80, v81
	v_cvt_pk_bf16_f32 v161, v82, v83
	ds_read_b64_tr_b16 v[80:81], v243 offset:28672
	ds_read_b64_tr_b16 v[82:83], v243 offset:29184
	v_add_f32_e32 v245, v86, v245
	v_add_f32_e32 v246, v87, v246
	v_add_f32_e32 v245, v88, v245
	v_add_f32_e32 v246, v89, v246
	v_cvt_pk_bf16_f32 v162, v84, v85
	v_cvt_pk_bf16_f32 v163, v86, v87
	ds_read_b64_tr_b16 v[84:85], v243 offset:25600
	ds_read_b64_tr_b16 v[86:87], v243 offset:26112
	v_add_f32_e32 v245, v90, v245
	v_add_f32_e32 v246, v91, v246
	v_add_f32_e32 v245, v92, v245
	v_add_f32_e32 v246, v93, v246
	v_cvt_pk_bf16_f32 v164, v88, v89
	v_cvt_pk_bf16_f32 v165, v90, v91
	ds_read_b64_tr_b16 v[88:89], v243 offset:29696
	ds_read_b64_tr_b16 v[90:91], v243 offset:30208
	v_add_f32_e32 v245, v94, v245
	v_add_f32_e32 v246, v95, v246
	v_add_f32_e32 v245, v96, v245
	v_add_f32_e32 v246, v97, v246
	v_cvt_pk_bf16_f32 v166, v92, v93
	v_cvt_pk_bf16_f32 v167, v94, v95
	ds_read_b64_tr_b16 v[92:93], v243 offset:26624
	ds_read_b64_tr_b16 v[94:95], v243 offset:27136
	v_add_f32_e32 v245, v98, v245
	v_add_f32_e32 v246, v99, v246
	v_add_f32_e32 v245, v100, v245
	v_add_f32_e32 v246, v101, v246
	v_cvt_pk_bf16_f32 v168, v96, v97
	v_cvt_pk_bf16_f32 v169, v98, v99
	ds_read_b64_tr_b16 v[96:97], v243 offset:30720
	ds_read_b64_tr_b16 v[98:99], v243 offset:31232
	v_add_f32_e32 v245, v102, v245
	v_add_f32_e32 v246, v103, v246
	v_add_f32_e32 v245, v104, v245
	v_add_f32_e32 v246, v105, v246
	v_cvt_pk_bf16_f32 v170, v100, v101
	v_cvt_pk_bf16_f32 v171, v102, v103
	ds_read_b64_tr_b16 v[100:101], v243 offset:27648
	ds_read_b64_tr_b16 v[102:103], v243 offset:28160
	v_add_f32_e32 v245, v106, v245
	v_add_f32_e32 v246, v107, v246
	v_add_f32_e32 v245, v108, v245
	v_add_f32_e32 v246, v109, v246
	v_cvt_pk_bf16_f32 v172, v104, v105
	v_cvt_pk_bf16_f32 v173, v106, v107
	ds_read_b64_tr_b16 v[104:105], v243 offset:31744
	ds_read_b64_tr_b16 v[106:107], v243 offset:32256
	v_add_f32_e32 v245, v110, v245
	v_add_f32_e32 v246, v111, v246
	v_add_f32_e32 v245, v245, v246
	v_cvt_pk_bf16_f32 v174, v108, v109
	v_cvt_pk_bf16_f32 v175, v110, v111
	v_add_f32_e32 v211, v211, v245
	s_waitcnt lgkmcnt(8)
	v_mfma_f32_32x32x16_bf16 v[0:15], v[160:163], v[214:217], v[0:15]
	ds_read_b64_tr_b16 v[214:215], v243 offset:49152
	ds_read_b64_tr_b16 v[216:217], v243 offset:49664
	v_mfma_f32_32x32x16_bf16 v[16:31], v[160:163], v[80:83], v[16:31]
	ds_read_b64_tr_b16 v[80:81], v243 offset:53248
	ds_read_b64_tr_b16 v[82:83], v243 offset:53760
	v_mfma_f32_32x32x16_bf16 v[0:15], v[164:167], v[84:87], v[0:15]
	s_add_i32 s21, s18, s54
	s_add_i32 m0, s21, 0x6000
	ds_read_b64_tr_b16 v[84:85], v243 offset:50176
	ds_read_b64_tr_b16 v[86:87], v243 offset:50688
	global_load_lds_dwordx4 v223, s[4:5]
	v_mfma_f32_32x32x16_bf16 v[16:31], v[164:167], v[88:91], v[16:31]
	s_add_i32 m0, s21, 0xc000
	ds_read_b64_tr_b16 v[88:89], v243 offset:54272
	ds_read_b64_tr_b16 v[90:91], v243 offset:54784
	global_load_lds_dwordx4 v224, s[4:5]
	s_add_u32 s4, s4, 0x20000
	s_addc_u32 s5, s5, 0
	s_waitcnt lgkmcnt(8)
	v_mfma_f32_32x32x16_bf16 v[0:15], v[168:171], v[92:95], v[0:15]
	ds_read_b64_tr_b16 v[92:93], v243 offset:51200
	ds_read_b64_tr_b16 v[94:95], v243 offset:51712
	v_mfma_f32_32x32x16_bf16 v[16:31], v[168:171], v[96:99], v[16:31]
	ds_read_b64_tr_b16 v[96:97], v243 offset:55296
	ds_read_b64_tr_b16 v[98:99], v243 offset:55808
	v_mfma_f32_32x32x16_bf16 v[0:15], v[172:175], v[100:103], v[0:15]
	ds_read_b64_tr_b16 v[100:101], v243 offset:52224
	ds_read_b64_tr_b16 v[102:103], v243 offset:52736
	v_mfma_f32_32x32x16_bf16 v[16:31], v[172:175], v[104:107], v[16:31]
	ds_read_b64_tr_b16 v[104:105], v243 offset:56320
	ds_read_b64_tr_b16 v[106:107], v243 offset:56832
	s_waitcnt lgkmcnt(8)
	v_mfma_f32_32x32x16_bf16 v[32:47], v[160:163], v[214:217], v[32:47]
	v_mfma_f32_32x32x16_bf16 v[48:63], v[160:163], v[80:83], v[48:63]
	v_mfma_f32_32x32x16_bf16 v[32:47], v[164:167], v[84:87], v[32:47]
	v_mfma_f32_32x32x16_bf16 v[48:63], v[164:167], v[88:91], v[48:63]
	s_waitcnt lgkmcnt(0)
	v_mfma_f32_32x32x16_bf16 v[32:47], v[168:171], v[92:95], v[32:47]
	v_mfma_f32_32x32x16_bf16 v[48:63], v[168:171], v[96:99], v[48:63]
	v_mfma_f32_32x32x16_bf16 v[32:47], v[172:175], v[100:103], v[32:47]
	v_mfma_f32_32x32x16_bf16 v[48:63], v[172:175], v[104:107], v[48:63]
	s_waitcnt vmcnt(2) lgkmcnt(0)
	s_barrier
	s_mov_b32 s21, s16
	s_mov_b32 s16, s17
	s_mov_b32 s17, s18
	s_mov_b32 s18, s21
	s_branch .Lat_T3_end

; __device__ __forceinline__ void cmask(f32x16&p0,f32x16&p1,int jb,int qrel,int hi){
;   const float NEG=-INFINITY; int kb=64*jb+4*hi;
;   #pragma unroll
;   for(int r=0;r<16;++r){int kv=kb+(r&3)+8*(r>>2); if(kv>qrel)p0[r]=NEG; if(kv+32>qrel)p1[r]=NEG;}
; }
.Lat_T3_end:
.Lat_step_T2:
	s_cmp_lt_u32 s55, 2
	s_cbranch_scc1 .Lat_T2_light
	v_add_u32_e32 v243, s16, v204
	ds_read_b64_tr_b16 v[214:215], v243 offset:24576
	ds_read_b64_tr_b16 v[216:217], v243 offset:25088
	v_mfma_f32_32x32x16_bf16 v[80:95], v[176:179], v[144:147], v[64:79]
	v_add_f32_e32 v245, v112, v113
	v_add_f32_e32 v246, v114, v115
	v_add_f32_e32 v245, v116, v245
	v_add_f32_e32 v246, v117, v246
	v_cvt_pk_bf16_f32 v160, v112, v113
	v_cvt_pk_bf16_f32 v161, v114, v115
	ds_read_b64_tr_b16 v[112:113], v243 offset:28672
	ds_read_b64_tr_b16 v[114:115], v243 offset:29184
	v_mfma_f32_32x32x16_bf16 v[96:111], v[180:183], v[144:147], v[64:79]
	v_add_f32_e32 v245, v118, v245
	v_add_f32_e32 v246, v119, v246
	v_add_f32_e32 v245, v120, v245
	v_add_f32_e32 v246, v121, v246
	v_cvt_pk_bf16_f32 v162, v116, v117
	v_cvt_pk_bf16_f32 v163, v118, v119
	ds_read_b64_tr_b16 v[116:117], v243 offset:25600
	ds_read_b64_tr_b16 v[118:119], v243 offset:26112
	v_mfma_f32_32x32x16_bf16 v[80:95], v[184:187], v[148:151], v[80:95]
	v_add_f32_e32 v245, v122, v245
	v_add_f32_e32 v246, v123, v246
	v_add_f32_e32 v245, v124, v245
	v_add_f32_e32 v246, v125, v246
	v_cvt_pk_bf16_f32 v164, v120, v121
	v_cvt_pk_bf16_f32 v165, v122, v123
	ds_read_b64_tr_b16 v[120:121], v243 offset:29696
	ds_read_b64_tr_b16 v[122:123], v243 offset:30208
	v_mfma_f32_32x32x16_bf16 v[96:111], v[188:191], v[148:151], v[96:111]
	v_add_f32_e32 v245, v126, v245
	v_add_f32_e32 v246, v127, v246
	v_add_f32_e32 v245, v128, v245
	v_add_f32_e32 v246, v129, v246
	v_cvt_pk_bf16_f32 v166, v124, v125
	v_cvt_pk_bf16_f32 v167, v126, v127
	ds_read_b64_tr_b16 v[124:125], v243 offset:26624
	ds_read_b64_tr_b16 v[126:127], v243 offset:27136
	v_mfma_f32_32x32x16_bf16 v[80:95], v[192:195], v[152:155], v[80:95]
	v_add_f32_e32 v245, v130, v245
	v_add_f32_e32 v246, v131, v246
	v_add_f32_e32 v245, v132, v245
	v_add_f32_e32 v246, v133, v246
	v_cvt_pk_bf16_f32 v168, v128, v129
	v_cvt_pk_bf16_f32 v169, v130, v131
	ds_read_b64_tr_b16 v[128:129], v243 offset:30720
	ds_read_b64_tr_b16 v[130:131], v243 offset:31232
	v_mfma_f32_32x32x16_bf16 v[96:111], v[196:199], v[152:155], v[96:111]
	v_add_f32_e32 v245, v134, v245
	v_add_f32_e32 v246, v135, v246
	v_add_f32_e32 v245, v136, v245
	v_add_f32_e32 v246, v137, v246
	v_cvt_pk_bf16_f32 v170, v132, v133
	v_cvt_pk_bf16_f32 v171, v134, v135
	ds_read_b64_tr_b16 v[132:133], v243 offset:27648
	ds_read_b64_tr_b16 v[134:135], v243 offset:28160
	v_mfma_f32_32x32x16_bf16 v[80:95], v[200:203], v[156:159], v[80:95]
	v_add_f32_e32 v245, v138, v245
	v_add_f32_e32 v246, v139, v246
	v_add_f32_e32 v245, v140, v245
	v_add_f32_e32 v246, v141, v246
	v_cvt_pk_bf16_f32 v172, v136, v137
	v_cvt_pk_bf16_f32 v173, v138, v139
	ds_read_b64_tr_b16 v[136:137], v243 offset:31744
	ds_read_b64_tr_b16 v[138:139], v243 offset:32256
	v_mfma_f32_32x32x16_bf16 v[96:111], v[206:209], v[156:159], v[96:111]
	v_add_f32_e32 v245, v142, v245
	v_add_f32_e32 v246, v143, v246
	v_add_f32_e32 v245, v245, v246
	v_cvt_pk_bf16_f32 v174, v140, v141
	v_cvt_pk_bf16_f32 v175, v142, v143
	v_add_f32_e32 v211, v211, v245
	v_add_u32_e32 v244, s18, v219
	s_waitcnt lgkmcnt(8)
	v_mfma_f32_32x32x16_bf16 v[0:15], v[160:163], v[214:217], v[0:15]
	v_add_u32_e32 v242, 0xffffff80, v225
	v_cmp_gt_i32_e64 s[28:29], 0, v242
	v_cmp_gt_i32_e64 s[30:31], 1, v242
	v_cmp_gt_i32_e64 s[34:35], 2, v242
	v_cndmask_b32_e64 v80, v80, v241, s[28:29]
	v_cmp_gt_i32_e64 s[28:29], 3, v242
	v_cndmask_b32_e64 v81, v81, v241, s[30:31]
	v_cmp_gt_i32_e64 s[30:31], 8, v242
	v_cndmask_b32_e64 v82, v82, v241, s[34:35]
	v_cmp_gt_i32_e64 s[34:35], 9, v242
	ds_read_b64_tr_b16 v[214:215], v243 offset:49152
	ds_read_b64_tr_b16 v[216:217], v243 offset:49664
	v_mfma_f32_32x32x16_bf16 v[16:31], v[160:163], v[112:115], v[16:31]
	v_cndmask_b32_e64 v83, v83, v241, s[28:29]
	v_cmp_gt_i32_e64 s[28:29], 10, v242
	v_cndmask_b32_e64 v84, v84, v241, s[30:31]
	v_cmp_gt_i32_e64 s[30:31], 11, v242
	v_cndmask_b32_e64 v85, v85, v241, s[34:35]
	v_cmp_gt_i32_e64 s[34:35], 16, v242
	v_cndmask_b32_e64 v86, v86, v241, s[28:29]
	v_cmp_gt_i32_e64 s[28:29], 17, v242
	v_cndmask_b32_e64 v87, v87, v241, s[30:31]
	v_cmp_gt_i32_e64 s[30:31], 18, v242
	ds_read_b64_tr_b16 v[112:113], v243 offset:53248
	ds_read_b64_tr_b16 v[114:115], v243 offset:53760
	v_mfma_f32_32x32x16_bf16 v[0:15], v[164:167], v[116:119], v[0:15]
	s_add_i32 s21, s18, s54
	s_add_i32 m0, s21, 0x6000
	v_cndmask_b32_e64 v88, v88, v241, s[34:35]
	v_cmp_gt_i32_e64 s[34:35], 19, v242
	v_cndmask_b32_e64 v89, v89, v241, s[28:29]
	v_cmp_gt_i32_e64 s[28:29], 24, v242
	v_cndmask_b32_e64 v90, v90, v241, s[30:31]
	v_cmp_gt_i32_e64 s[30:31], 25, v242
	v_cndmask_b32_e64 v91, v91, v241, s[34:35]
	v_cmp_gt_i32_e64 s[34:35], 26, v242
	v_cndmask_b32_e64 v92, v92, v241, s[28:29]
	v_cmp_gt_i32_e64 s[28:29], 27, v242
	ds_read_b64_tr_b16 v[116:117], v243 offset:50176
	ds_read_b64_tr_b16 v[118:119], v243 offset:50688
	global_load_lds_dwordx4 v223, s[4:5]
	v_mfma_f32_32x32x16_bf16 v[16:31], v[164:167], v[120:123], v[16:31]
	s_add_i32 m0, s21, 0xc000
	v_cndmask_b32_e64 v93, v93, v241, s[30:31]
	v_cmp_gt_i32_e64 s[30:31], 32, v242
	v_cndmask_b32_e64 v94, v94, v241, s[34:35]
	v_cmp_gt_i32_e64 s[34:35], 33, v242
	v_cndmask_b32_e64 v95, v95, v241, s[28:29]
	v_cmp_gt_i32_e64 s[28:29], 34, v242
	v_cndmask_b32_e64 v96, v96, v241, s[30:31]
	v_cmp_gt_i32_e64 s[30:31], 35, v242
	v_cndmask_b32_e64 v97, v97, v241, s[34:35]
	v_cmp_gt_i32_e64 s[34:35], 40, v242
	ds_read_b64_tr_b16 v[120:121], v243 offset:54272
	ds_read_b64_tr_b16 v[122:123], v243 offset:54784
	global_load_lds_dwordx4 v224, s[4:5]
	s_add_u32 s4, s4, 0x20000
	s_addc_u32 s5, s5, 0
	s_waitcnt lgkmcnt(8)
; __device__ __forceinline__ void cmask(f32x16&p0,f32x16&p1,int jb,int qrel,int hi){
;   const float NEG=-INFINITY; int kb=64*jb+4*hi;
;   #pragma unroll
;   for(int r=0;r<16;++r){int kv=kb+(r&3)+8*(r>>2); if(kv>qrel)p0[r]=NEG; if(kv+32>qrel)p1[r]=NEG;}
; }
	v_mfma_f32_32x32x16_bf16 v[0:15], v[168:171], v[124:127], v[0:15]
	v_cndmask_b32_e64 v98, v98, v241, s[28:29]
	v_cmp_gt_i32_e64 s[28:29], 41, v242
	v_cndmask_b32_e64 v99, v99, v241, s[30:31]
	v_cmp_gt_i32_e64 s[30:31], 42, v242
	v_cndmask_b32_e64 v100, v100, v241, s[34:35]
	v_cmp_gt_i32_e64 s[34:35], 43, v242
	v_cndmask_b32_e64 v101, v101, v241, s[28:29]
	v_cmp_gt_i32_e64 s[28:29], 48, v242
	v_cndmask_b32_e64 v102, v102, v241, s[30:31]
	v_cmp_gt_i32_e64 s[30:31], 49, v242
	ds_read_b64_tr_b16 v[124:125], v243 offset:51200
	ds_read_b64_tr_b16 v[126:127], v243 offset:51712
	v_mfma_f32_32x32x16_bf16 v[16:31], v[168:171], v[128:131], v[16:31]
	v_cndmask_b32_e64 v103, v103, v241, s[34:35]
	v_cmp_gt_i32_e64 s[34:35], 50, v242
	v_cndmask_b32_e64 v104, v104, v241, s[28:29]
	v_cmp_gt_i32_e64 s[28:29], 51, v242
	v_cndmask_b32_e64 v105, v105, v241, s[30:31]
	v_cmp_gt_i32_e64 s[30:31], 56, v242
	v_cndmask_b32_e64 v106, v106, v241, s[34:35]
	v_cmp_gt_i32_e64 s[34:35], 57, v242
	v_cndmask_b32_e64 v107, v107, v241, s[28:29]
	v_cmp_gt_i32_e64 s[28:29], 58, v242
	ds_read_b64_tr_b16 v[128:129], v243 offset:55296
	ds_read_b64_tr_b16 v[130:131], v243 offset:55808
	v_mfma_f32_32x32x16_bf16 v[0:15], v[172:175], v[132:135], v[0:15]
	v_cndmask_b32_e64 v108, v108, v241, s[30:31]
	v_cmp_gt_i32_e64 s[30:31], 59, v242
	v_cndmask_b32_e64 v109, v109, v241, s[34:35]
	v_cndmask_b32_e64 v110, v110, v241, s[28:29]
	v_cndmask_b32_e64 v111, v111, v241, s[30:31]
	v_max3_f32 v246, v80, v81, v82
	v_max3_f32 v247, v83, v84, v85
	v_max3_f32 v246, v246, v86, v87
	v_max3_f32 v247, v247, v88, v89
	v_max3_f32 v246, v246, v90, v91
	ds_read_b64_tr_b16 v[132:133], v243 offset:52224
	ds_read_b64_tr_b16 v[134:135], v243 offset:52736
	v_mfma_f32_32x32x16_bf16 v[16:31], v[172:175], v[136:139], v[16:31]
	v_max3_f32 v247, v247, v92, v93
	v_max3_f32 v246, v246, v94, v95
	v_max3_f32 v247, v247, v96, v97
	v_max3_f32 v246, v246, v98, v99
	v_max3_f32 v247, v247, v100, v101
	v_max3_f32 v246, v246, v102, v103
	v_max3_f32 v247, v247, v104, v105
	v_max3_f32 v246, v246, v106, v107
	v_max3_f32 v247, v247, v108, v109
	v_max3_f32 v246, v246, v110, v111
	ds_read_b64_tr_b16 v[136:137], v243 offset:56320
	ds_read_b64_tr_b16 v[138:139], v243 offset:56832
	s_waitcnt lgkmcnt(8)
	v_mfma_f32_32x32x16_bf16 v[32:47], v[160:163], v[214:217], v[32:47]
	v_max_f32_e32 v248, v246, v247
	ds_read_b128 v[176:179], v244 offset:0
	ds_read_b128 v[180:183], v244 offset:512
	v_cmp_lt_f32_e32 vcc, s87, v248
	s_cbranch_vccnz .Lat_rare_T2
.Lat_cont_T2:
	v_mfma_f32_32x32x16_bf16 v[48:63], v[160:163], v[112:115], v[48:63]
	v_exp_f32_e32 v80, v80
	v_exp_f32_e32 v81, v81
	v_exp_f32_e32 v82, v82
	v_exp_f32_e32 v83, v83
	v_exp_f32_e32 v84, v84
	ds_read_b128 v[184:187], v244 offset:2048
	ds_read_b128 v[188:191], v244 offset:2560
	v_mfma_f32_32x32x16_bf16 v[32:47], v[164:167], v[116:119], v[32:47]
	v_exp_f32_e32 v85, v85
	v_exp_f32_e32 v86, v86
	v_exp_f32_e32 v87, v87
	v_exp_f32_e32 v88, v88
	v_exp_f32_e32 v89, v89
	ds_read_b128 v[192:195], v244 offset:4096
	ds_read_b128 v[196:199], v244 offset:4608
	v_mfma_f32_32x32x16_bf16 v[48:63], v[164:167], v[120:123], v[48:63]
	v_exp_f32_e32 v90, v90
	v_exp_f32_e32 v91, v91
	v_exp_f32_e32 v92, v92
	v_exp_f32_e32 v93, v93
	v_exp_f32_e32 v94, v94
	ds_read_b128 v[200:203], v244 offset:6144
	ds_read_b128 v[206:209], v244 offset:6656
	s_waitcnt lgkmcnt(8)
	v_mfma_f32_32x32x16_bf16 v[32:47], v[168:171], v[124:127], v[32:47]
	v_exp_f32_e32 v95, v95
	v_exp_f32_e32 v96, v96
	v_exp_f32_e32 v97, v97
	v_exp_f32_e32 v98, v98
	v_exp_f32_e32 v99, v99
	v_mfma_f32_32x32x16_bf16 v[48:63], v[168:171], v[128:131], v[48:63]
	v_exp_f32_e32 v100, v100
	v_exp_f32_e32 v101, v101
	v_exp_f32_e32 v102, v102
	v_exp_f32_e32 v103, v103
	v_mfma_f32_32x32x16_bf16 v[32:47], v[172:175], v[132:135], v[32:47]
	v_exp_f32_e32 v104, v104
	v_exp_f32_e32 v105, v105
	v_exp_f32_e32 v106, v106
	v_exp_f32_e32 v107, v107
	v_mfma_f32_32x32x16_bf16 v[48:63], v[172:175], v[136:139], v[48:63]
	v_exp_f32_e32 v108, v108
	v_exp_f32_e32 v109, v109
	v_exp_f32_e32 v110, v110
	v_exp_f32_e32 v111, v111
	s_waitcnt vmcnt(0) lgkmcnt(0)
	s_barrier
	s_cbranch_vccnz .Lat_resc_T2

.Lat_T2_light:
	s_cmp_lt_u32 s55, 1
	s_cbranch_scc1 .Lat_T2_empty
	v_add_u32_e32 v243, s16, v204
	ds_read_b64_tr_b16 v[214:215], v243 offset:24576
	ds_read_b64_tr_b16 v[216:217], v243 offset:25088
	v_add_f32_e32 v245, v112, v113
	v_add_f32_e32 v246, v114, v115
	v_add_f32_e32 v245, v116, v245
	v_add_f32_e32 v246, v117, v246
	v_cvt_pk_bf16_f32 v160, v112, v113
	v_cvt_pk_bf16_f32 v161, v114, v115
	ds_read_b64_tr_b16 v[112:113], v243 offset:28672
	ds_read_b64_tr_b16 v[114:115], v243 offset:29184
	v_add_f32_e32 v245, v118, v245
	v_add_f32_e32 v246, v119, v246
	v_add_f32_e32 v245, v120, v245
	v_add_f32_e32 v246, v121, v246
	v_cvt_pk_bf16_f32 v162, v116, v117
	v_cvt_pk_bf16_f32 v163, v118, v119
	ds_read_b64_tr_b16 v[116:117], v243 offset:25600
	ds_read_b64_tr_b16 v[118:119], v243 offset:26112
	v_add_f32_e32 v245, v122, v245
	v_add_f32_e32 v246, v123, v246
	v_add_f32_e32 v245, v124, v245
	v_add_f32_e32 v246, v125, v246
	v_cvt_pk_bf16_f32 v164, v120, v121
	v_cvt_pk_bf16_f32 v165, v122, v123
	ds_read_b64_tr_b16 v[120:121], v243 offset:29696
	ds_read_b64_tr_b16 v[122:123], v243 offset:30208
	v_add_f32_e32 v245, v126, v245
	v_add_f32_e32 v246, v127, v246
	v_add_f32_e32 v245, v128, v245
	v_add_f32_e32 v246, v129, v246
	v_cvt_pk_bf16_f32 v166, v124, v125
	v_cvt_pk_bf16_f32 v167, v126, v127
	ds_read_b64_tr_b16 v[124:125], v243 offset:26624
	ds_read_b64_tr_b16 v[126:127], v243 offset:27136
	v_add_f32_e32 v245, v130, v245
	v_add_f32_e32 v246, v131, v246
	v_add_f32_e32 v245, v132, v245
	v_add_f32_e32 v246, v133, v246
	v_cvt_pk_bf16_f32 v168, v128, v129
	v_cvt_pk_bf16_f32 v169, v130, v131
	ds_read_b64_tr_b16 v[128:129], v243 offset:30720
	ds_read_b64_tr_b16 v[130:131], v243 offset:31232
	v_add_f32_e32 v245, v134, v245
	v_add_f32_e32 v246, v135, v246
	v_add_f32_e32 v245, v136, v245
	v_add_f32_e32 v246, v137, v246
	v_cvt_pk_bf16_f32 v170, v132, v133
	v_cvt_pk_bf16_f32 v171, v134, v135
	ds_read_b64_tr_b16 v[132:133], v243 offset:27648
	ds_read_b64_tr_b16 v[134:135], v243 offset:28160
	v_add_f32_e32 v245, v138, v245
	v_add_f32_e32 v246, v139, v246
	v_add_f32_e32 v245, v140, v245
	v_add_f32_e32 v246, v141, v246
	v_cvt_pk_bf16_f32 v172, v136, v137
	v_cvt_pk_bf16_f32 v173, v138, v139
	ds_read_b64_tr_b16 v[136:137], v243 offset:31744
	ds_read_b64_tr_b16 v[138:139], v243 offset:32256
	v_add_f32_e32 v245, v142, v245
	v_add_f32_e32 v246, v143, v246
	v_add_f32_e32 v245, v245, v246
	v_cvt_pk_bf16_f32 v174, v140, v141
	v_cvt_pk_bf16_f32 v175, v142, v143
	v_add_f32_e32 v211, v211, v245
	s_waitcnt lgkmcnt(8)
	v_mfma_f32_32x32x16_bf16 v[0:15], v[160:163], v[214:217], v[0:15]
	ds_read_b64_tr_b16 v[214:215], v243 offset:49152
	ds_read_b64_tr_b16 v[216:217], v243 offset:49664
	v_mfma_f32_32x32x16_bf16 v[16:31], v[160:163], v[112:115], v[16:31]
	ds_read_b64_tr_b16 v[112:113], v243 offset:53248
	ds_read_b64_tr_b16 v[114:115], v243 offset:53760
	v_mfma_f32_32x32x16_bf16 v[0:15], v[164:167], v[116:119], v[0:15]
	s_add_i32 s21, s18, s54
	s_add_i32 m0, s21, 0x6000
	ds_read_b64_tr_b16 v[116:117], v243 offset:50176
	ds_read_b64_tr_b16 v[118:119], v243 offset:50688
	global_load_lds_dwordx4 v223, s[4:5]
	v_mfma_f32_32x32x16_bf16 v[16:31], v[164:167], v[120:123], v[16:31]
	s_add_i32 m0, s21, 0xc000
	ds_read_b64_tr_b16 v[120:121], v243 offset:54272
	ds_read_b64_tr_b16 v[122:123], v243 offset:54784
	global_load_lds_dwordx4 v224, s[4:5]
	s_add_u32 s4, s4, 0x20000
	s_addc_u32 s5, s5, 0
	s_waitcnt lgkmcnt(8)
	v_mfma_f32_32x32x16_bf16 v[0:15], v[168:171], v[124:127], v[0:15]
	ds_read_b64_tr_b16 v[124:125], v243 offset:51200
	ds_read_b64_tr_b16 v[126:127], v243 offset:51712
	v_mfma_f32_32x32x16_bf16 v[16:31], v[168:171], v[128:131], v[16:31]
	ds_read_b64_tr_b16 v[128:129], v243 offset:55296
	ds_read_b64_tr_b16 v[130:131], v243 offset:55808
	v_mfma_f32_32x32x16_bf16 v[0:15], v[172:175], v[132:135], v[0:15]
	ds_read_b64_tr_b16 v[132:133], v243 offset:52224
	ds_read_b64_tr_b16 v[134:135], v243 offset:52736
	v_mfma_f32_32x32x16_bf16 v[16:31], v[172:175], v[136:139], v[16:31]
	ds_read_b64_tr_b16 v[136:137], v243 offset:56320
	ds_read_b64_tr_b16 v[138:139], v243 offset:56832
	s_waitcnt lgkmcnt(8)
	v_mfma_f32_32x32x16_bf16 v[32:47], v[160:163], v[214:217], v[32:47]
	v_mfma_f32_32x32x16_bf16 v[48:63], v[160:163], v[112:115], v[48:63]
	v_mfma_f32_32x32x16_bf16 v[32:47], v[164:167], v[116:119], v[32:47]
	v_mfma_f32_32x32x16_bf16 v[48:63], v[164:167], v[120:123], v[48:63]
	s_waitcnt lgkmcnt(0)
	v_mfma_f32_32x32x16_bf16 v[32:47], v[168:171], v[124:127], v[32:47]
	v_mfma_f32_32x32x16_bf16 v[48:63], v[168:171], v[128:131], v[48:63]
	v_mfma_f32_32x32x16_bf16 v[32:47], v[172:175], v[132:135], v[32:47]
	v_mfma_f32_32x32x16_bf16 v[48:63], v[172:175], v[136:139], v[48:63]
	s_waitcnt vmcnt(0) lgkmcnt(0)
	s_barrier
	s_mov_b32 s21, s16
	s_mov_b32 s16, s17
	s_mov_b32 s17, s18
	s_mov_b32 s18, s21
	s_branch .Lat_T2_end

; __device__ __forceinline__ void cmask(f32x16&p0,f32x16&p1,int jb,int qrel,int hi){
;   const float NEG=-INFINITY; int kb=64*jb+4*hi;
;   #pragma unroll
;   for(int r=0;r<16;++r){int kv=kb+(r&3)+8*(r>>2); if(kv>qrel)p0[r]=NEG; if(kv+32>qrel)p1[r]=NEG;}
; }
.Lat_T2_end:
.Lat_step_T1:
	s_cmp_lt_u32 s55, 3
	s_cbranch_scc1 .Lat_T1_light
	v_add_u32_e32 v243, s16, v204
	ds_read_b64_tr_b16 v[214:215], v243 offset:24576
	ds_read_b64_tr_b16 v[216:217], v243 offset:25088
	v_mfma_f32_32x32x16_bf16 v[112:127], v[176:179], v[144:147], v[64:79]
	v_add_f32_e32 v245, v80, v81
	v_add_f32_e32 v246, v82, v83
	v_add_f32_e32 v245, v84, v245
	v_add_f32_e32 v246, v85, v246
	v_cvt_pk_bf16_f32 v160, v80, v81
	v_cvt_pk_bf16_f32 v161, v82, v83
	ds_read_b64_tr_b16 v[80:81], v243 offset:28672
	ds_read_b64_tr_b16 v[82:83], v243 offset:29184
	v_mfma_f32_32x32x16_bf16 v[128:143], v[180:183], v[144:147], v[64:79]
	v_add_f32_e32 v245, v86, v245
	v_add_f32_e32 v246, v87, v246
	v_add_f32_e32 v245, v88, v245
	v_add_f32_e32 v246, v89, v246
	v_cvt_pk_bf16_f32 v162, v84, v85
	v_cvt_pk_bf16_f32 v163, v86, v87
	ds_read_b64_tr_b16 v[84:85], v243 offset:25600
	ds_read_b64_tr_b16 v[86:87], v243 offset:26112
	v_mfma_f32_32x32x16_bf16 v[112:127], v[184:187], v[148:151], v[112:127]
	v_add_f32_e32 v245, v90, v245
	v_add_f32_e32 v246, v91, v246
	v_add_f32_e32 v245, v92, v245
	v_add_f32_e32 v246, v93, v246
	v_cvt_pk_bf16_f32 v164, v88, v89
	v_cvt_pk_bf16_f32 v165, v90, v91
	ds_read_b64_tr_b16 v[88:89], v243 offset:29696
	ds_read_b64_tr_b16 v[90:91], v243 offset:30208
	v_mfma_f32_32x32x16_bf16 v[128:143], v[188:191], v[148:151], v[128:143]
	v_add_f32_e32 v245, v94, v245
	v_add_f32_e32 v246, v95, v246
	v_add_f32_e32 v245, v96, v245
	v_add_f32_e32 v246, v97, v246
	v_cvt_pk_bf16_f32 v166, v92, v93
	v_cvt_pk_bf16_f32 v167, v94, v95
	ds_read_b64_tr_b16 v[92:93], v243 offset:26624
	ds_read_b64_tr_b16 v[94:95], v243 offset:27136
	v_mfma_f32_32x32x16_bf16 v[112:127], v[192:195], v[152:155], v[112:127]
	v_add_f32_e32 v245, v98, v245
	v_add_f32_e32 v246, v99, v246
	v_add_f32_e32 v245, v100, v245
	v_add_f32_e32 v246, v101, v246
	v_cvt_pk_bf16_f32 v168, v96, v97
	v_cvt_pk_bf16_f32 v169, v98, v99
	ds_read_b64_tr_b16 v[96:97], v243 offset:30720
	ds_read_b64_tr_b16 v[98:99], v243 offset:31232
	v_mfma_f32_32x32x16_bf16 v[128:143], v[196:199], v[152:155], v[128:143]
	v_add_f32_e32 v245, v102, v245
	v_add_f32_e32 v246, v103, v246
	v_add_f32_e32 v245, v104, v245
	v_add_f32_e32 v246, v105, v246
	v_cvt_pk_bf16_f32 v170, v100, v101
	v_cvt_pk_bf16_f32 v171, v102, v103
	ds_read_b64_tr_b16 v[100:101], v243 offset:27648
	ds_read_b64_tr_b16 v[102:103], v243 offset:28160
	v_mfma_f32_32x32x16_bf16 v[112:127], v[200:203], v[156:159], v[112:127]
	v_add_f32_e32 v245, v106, v245
	v_add_f32_e32 v246, v107, v246
	v_add_f32_e32 v245, v108, v245
	v_add_f32_e32 v246, v109, v246
	v_cvt_pk_bf16_f32 v172, v104, v105
	v_cvt_pk_bf16_f32 v173, v106, v107
	ds_read_b64_tr_b16 v[104:105], v243 offset:31744
	ds_read_b64_tr_b16 v[106:107], v243 offset:32256
	v_mfma_f32_32x32x16_bf16 v[128:143], v[206:209], v[156:159], v[128:143]
	v_add_f32_e32 v245, v110, v245
	v_add_f32_e32 v246, v111, v246
	v_add_f32_e32 v245, v245, v246
	v_cvt_pk_bf16_f32 v174, v108, v109
	v_cvt_pk_bf16_f32 v175, v110, v111
	v_add_f32_e32 v211, v211, v245
	s_waitcnt lgkmcnt(8)
	v_mfma_f32_32x32x16_bf16 v[0:15], v[160:163], v[214:217], v[0:15]
	v_add_u32_e32 v242, 0xffffff40, v225
	v_cmp_gt_i32_e64 s[28:29], 0, v242
	v_cmp_gt_i32_e64 s[30:31], 1, v242
	v_cmp_gt_i32_e64 s[34:35], 2, v242
	v_cndmask_b32_e64 v112, v112, v241, s[28:29]
	v_cmp_gt_i32_e64 s[28:29], 3, v242
	v_cndmask_b32_e64 v113, v113, v241, s[30:31]
	v_cmp_gt_i32_e64 s[30:31], 8, v242
	v_cndmask_b32_e64 v114, v114, v241, s[34:35]
	v_cmp_gt_i32_e64 s[34:35], 9, v242
	ds_read_b64_tr_b16 v[214:215], v243 offset:49152
	ds_read_b64_tr_b16 v[216:217], v243 offset:49664
	v_mfma_f32_32x32x16_bf16 v[16:31], v[160:163], v[80:83], v[16:31]
	v_cndmask_b32_e64 v115, v115, v241, s[28:29]
	v_cmp_gt_i32_e64 s[28:29], 10, v242
	v_cndmask_b32_e64 v116, v116, v241, s[30:31]
	v_cmp_gt_i32_e64 s[30:31], 11, v242
	v_cndmask_b32_e64 v117, v117, v241, s[34:35]
	v_cmp_gt_i32_e64 s[34:35], 16, v242
	v_cndmask_b32_e64 v118, v118, v241, s[28:29]
	v_cmp_gt_i32_e64 s[28:29], 17, v242
	v_cndmask_b32_e64 v119, v119, v241, s[30:31]
	v_cmp_gt_i32_e64 s[30:31], 18, v242
	ds_read_b64_tr_b16 v[80:81], v243 offset:53248
	ds_read_b64_tr_b16 v[82:83], v243 offset:53760
	v_mfma_f32_32x32x16_bf16 v[0:15], v[164:167], v[84:87], v[0:15]
	v_cndmask_b32_e64 v120, v120, v241, s[34:35]
	v_cmp_gt_i32_e64 s[34:35], 19, v242
	v_cndmask_b32_e64 v121, v121, v241, s[28:29]
	v_cmp_gt_i32_e64 s[28:29], 24, v242
	v_cndmask_b32_e64 v122, v122, v241, s[30:31]
	v_cmp_gt_i32_e64 s[30:31], 25, v242
	v_cndmask_b32_e64 v123, v123, v241, s[34:35]
	v_cmp_gt_i32_e64 s[34:35], 26, v242
	v_cndmask_b32_e64 v124, v124, v241, s[28:29]
	v_cmp_gt_i32_e64 s[28:29], 27, v242
	ds_read_b64_tr_b16 v[84:85], v243 offset:50176
	ds_read_b64_tr_b16 v[86:87], v243 offset:50688
	v_mfma_f32_32x32x16_bf16 v[16:31], v[164:167], v[88:91], v[16:31]
	v_cndmask_b32_e64 v125, v125, v241, s[30:31]
	v_cmp_gt_i32_e64 s[30:31], 32, v242
	v_cndmask_b32_e64 v126, v126, v241, s[34:35]
	v_cmp_gt_i32_e64 s[34:35], 33, v242
	v_cndmask_b32_e64 v127, v127, v241, s[28:29]
	v_cmp_gt_i32_e64 s[28:29], 34, v242
	v_cndmask_b32_e64 v128, v128, v241, s[30:31]
	v_cmp_gt_i32_e64 s[30:31], 35, v242
	v_cndmask_b32_e64 v129, v129, v241, s[34:35]
	v_cmp_gt_i32_e64 s[34:35], 40, v242
	ds_read_b64_tr_b16 v[88:89], v243 offset:54272
	ds_read_b64_tr_b16 v[90:91], v243 offset:54784
	s_waitcnt lgkmcnt(8)
	v_mfma_f32_32x32x16_bf16 v[0:15], v[168:171], v[92:95], v[0:15]
	v_cndmask_b32_e64 v130, v130, v241, s[28:29]
	v_cmp_gt_i32_e64 s[28:29], 41, v242
	v_cndmask_b32_e64 v131, v131, v241, s[30:31]
	v_cmp_gt_i32_e64 s[30:31], 42, v242
	v_cndmask_b32_e64 v132, v132, v241, s[34:35]
	v_cmp_gt_i32_e64 s[34:35], 43, v242
	v_cndmask_b32_e64 v133, v133, v241, s[28:29]
	v_cmp_gt_i32_e64 s[28:29], 48, v242
	v_cndmask_b32_e64 v134, v134, v241, s[30:31]
	v_cmp_gt_i32_e64 s[30:31], 49, v242
	ds_read_b64_tr_b16 v[92:93], v243 offset:51200
	ds_read_b64_tr_b16 v[94:95], v243 offset:51712
	v_mfma_f32_32x32x16_bf16 v[16:31], v[168:171], v[96:99], v[16:31]
	v_cndmask_b32_e64 v135, v135, v241, s[34:35]
	v_cmp_gt_i32_e64 s[34:35], 50, v242
	v_cndmask_b32_e64 v136, v136, v241, s[28:29]
	v_cmp_gt_i32_e64 s[28:29], 51, v242
	v_cndmask_b32_e64 v137, v137, v241, s[30:31]
	v_cmp_gt_i32_e64 s[30:31], 56, v242
	v_cndmask_b32_e64 v138, v138, v241, s[34:35]
	v_cmp_gt_i32_e64 s[34:35], 57, v242
	v_cndmask_b32_e64 v139, v139, v241, s[28:29]
	v_cmp_gt_i32_e64 s[28:29], 58, v242
	ds_read_b64_tr_b16 v[96:97], v243 offset:55296
	ds_read_b64_tr_b16 v[98:99], v243 offset:55808
	v_mfma_f32_32x32x16_bf16 v[0:15], v[172:175], v[100:103], v[0:15]
	v_cndmask_b32_e64 v140, v140, v241, s[30:31]
	v_cmp_gt_i32_e64 s[30:31], 59, v242
	v_cndmask_b32_e64 v141, v141, v241, s[34:35]
	v_cndmask_b32_e64 v142, v142, v241, s[28:29]
	v_cndmask_b32_e64 v143, v143, v241, s[30:31]
	v_max3_f32 v246, v112, v113, v114
	v_max3_f32 v247, v115, v116, v117
	v_max3_f32 v246, v246, v118, v119
	v_max3_f32 v247, v247, v120, v121
	v_max3_f32 v246, v246, v122, v123
	ds_read_b64_tr_b16 v[100:101], v243 offset:52224
	ds_read_b64_tr_b16 v[102:103], v243 offset:52736
	v_mfma_f32_32x32x16_bf16 v[16:31], v[172:175], v[104:107], v[16:31]
	v_max3_f32 v247, v247, v124, v125
	v_max3_f32 v246, v246, v126, v127
	v_max3_f32 v247, v247, v128, v129
	v_max3_f32 v246, v246, v130, v131
	v_max3_f32 v247, v247, v132, v133
	v_max3_f32 v246, v246, v134, v135
	v_max3_f32 v247, v247, v136, v137
	v_max3_f32 v246, v246, v138, v139
	v_max3_f32 v247, v247, v140, v141
	v_max3_f32 v246, v246, v142, v143
	ds_read_b64_tr_b16 v[104:105], v243 offset:56320
	ds_read_b64_tr_b16 v[106:107], v243 offset:56832
	s_waitcnt lgkmcnt(8)
	v_mfma_f32_32x32x16_bf16 v[32:47], v[160:163], v[214:217], v[32:47]
	v_max_f32_e32 v248, v246, v247
	v_cmp_lt_f32_e32 vcc, s87, v248
	s_cbranch_vccnz .Lat_rare_T1
.Lat_cont_T1:
	v_mfma_f32_32x32x16_bf16 v[48:63], v[160:163], v[80:83], v[48:63]
	v_exp_f32_e32 v112, v112
	v_exp_f32_e32 v113, v113
	v_exp_f32_e32 v114, v114
	v_exp_f32_e32 v115, v115
	v_exp_f32_e32 v116, v116
	v_mfma_f32_32x32x16_bf16 v[32:47], v[164:167], v[84:87], v[32:47]
	v_exp_f32_e32 v117, v117
	v_exp_f32_e32 v118, v118
	v_exp_f32_e32 v119, v119
	v_exp_f32_e32 v120, v120
	v_exp_f32_e32 v121, v121
	v_mfma_f32_32x32x16_bf16 v[48:63], v[164:167], v[88:91], v[48:63]
	v_exp_f32_e32 v122, v122
	v_exp_f32_e32 v123, v123
	v_exp_f32_e32 v124, v124
	v_exp_f32_e32 v125, v125
	v_exp_f32_e32 v126, v126
	s_waitcnt lgkmcnt(0)
	v_mfma_f32_32x32x16_bf16 v[32:47], v[168:171], v[92:95], v[32:47]
	v_exp_f32_e32 v127, v127
	v_exp_f32_e32 v128, v128
	v_exp_f32_e32 v129, v129
	v_exp_f32_e32 v130, v130
	v_exp_f32_e32 v131, v131
	v_mfma_f32_32x32x16_bf16 v[48:63], v[168:171], v[96:99], v[48:63]
	v_exp_f32_e32 v132, v132
	v_exp_f32_e32 v133, v133
	v_exp_f32_e32 v134, v134
	v_exp_f32_e32 v135, v135
	v_mfma_f32_32x32x16_bf16 v[32:47], v[172:175], v[100:103], v[32:47]
	v_exp_f32_e32 v136, v136
	v_exp_f32_e32 v137, v137
	v_exp_f32_e32 v138, v138
	v_exp_f32_e32 v139, v139
	v_mfma_f32_32x32x16_bf16 v[48:63], v[172:175], v[104:107], v[48:63]
	v_exp_f32_e32 v140, v140
	v_exp_f32_e32 v141, v141
	v_exp_f32_e32 v142, v142
	v_exp_f32_e32 v143, v143
	s_cbranch_vccnz .Lat_resc_T1

.Lat_T1_light:
	s_cmp_lt_u32 s55, 2
	s_cbranch_scc1 .Lat_T1_empty
	v_add_u32_e32 v243, s16, v204
	ds_read_b64_tr_b16 v[214:215], v243 offset:24576
	ds_read_b64_tr_b16 v[216:217], v243 offset:25088
	v_add_f32_e32 v245, v80, v81
	v_add_f32_e32 v246, v82, v83
	v_add_f32_e32 v245, v84, v245
	v_add_f32_e32 v246, v85, v246
	v_cvt_pk_bf16_f32 v160, v80, v81
	v_cvt_pk_bf16_f32 v161, v82, v83
	ds_read_b64_tr_b16 v[80:81], v243 offset:28672
	ds_read_b64_tr_b16 v[82:83], v243 offset:29184
	v_add_f32_e32 v245, v86, v245
	v_add_f32_e32 v246, v87, v246
	v_add_f32_e32 v245, v88, v245
	v_add_f32_e32 v246, v89, v246
	v_cvt_pk_bf16_f32 v162, v84, v85
	v_cvt_pk_bf16_f32 v163, v86, v87
	ds_read_b64_tr_b16 v[84:85], v243 offset:25600
	ds_read_b64_tr_b16 v[86:87], v243 offset:26112
	v_add_f32_e32 v245, v90, v245
	v_add_f32_e32 v246, v91, v246
	v_add_f32_e32 v245, v92, v245
	v_add_f32_e32 v246, v93, v246
	v_cvt_pk_bf16_f32 v164, v88, v89
	v_cvt_pk_bf16_f32 v165, v90, v91
	ds_read_b64_tr_b16 v[88:89], v243 offset:29696
	ds_read_b64_tr_b16 v[90:91], v243 offset:30208
	v_add_f32_e32 v245, v94, v245
	v_add_f32_e32 v246, v95, v246
	v_add_f32_e32 v245, v96, v245
	v_add_f32_e32 v246, v97, v246
	v_cvt_pk_bf16_f32 v166, v92, v93
	v_cvt_pk_bf16_f32 v167, v94, v95
	ds_read_b64_tr_b16 v[92:93], v243 offset:26624
	ds_read_b64_tr_b16 v[94:95], v243 offset:27136
	v_add_f32_e32 v245, v98, v245
	v_add_f32_e32 v246, v99, v246
	v_add_f32_e32 v245, v100, v245
	v_add_f32_e32 v246, v101, v246
	v_cvt_pk_bf16_f32 v168, v96, v97
	v_cvt_pk_bf16_f32 v169, v98, v99
	ds_read_b64_tr_b16 v[96:97], v243 offset:30720
	ds_read_b64_tr_b16 v[98:99], v243 offset:31232
	v_add_f32_e32 v245, v102, v245
	v_add_f32_e32 v246, v103, v246
	v_add_f32_e32 v245, v104, v245
	v_add_f32_e32 v246, v105, v246
	v_cvt_pk_bf16_f32 v170, v100, v101
	v_cvt_pk_bf16_f32 v171, v102, v103
	ds_read_b64_tr_b16 v[100:101], v243 offset:27648
	ds_read_b64_tr_b16 v[102:103], v243 offset:28160
	v_add_f32_e32 v245, v106, v245
	v_add_f32_e32 v246, v107, v246
	v_add_f32_e32 v245, v108, v245
	v_add_f32_e32 v246, v109, v246
	v_cvt_pk_bf16_f32 v172, v104, v105
	v_cvt_pk_bf16_f32 v173, v106, v107
	ds_read_b64_tr_b16 v[104:105], v243 offset:31744
	ds_read_b64_tr_b16 v[106:107], v243 offset:32256
	v_add_f32_e32 v245, v110, v245
	v_add_f32_e32 v246, v111, v246
	v_add_f32_e32 v245, v245, v246
	v_cvt_pk_bf16_f32 v174, v108, v109
	v_cvt_pk_bf16_f32 v175, v110, v111
	v_add_f32_e32 v211, v211, v245
	s_waitcnt lgkmcnt(8)
	v_mfma_f32_32x32x16_bf16 v[0:15], v[160:163], v[214:217], v[0:15]
	ds_read_b64_tr_b16 v[214:215], v243 offset:49152
	ds_read_b64_tr_b16 v[216:217], v243 offset:49664
	v_mfma_f32_32x32x16_bf16 v[16:31], v[160:163], v[80:83], v[16:31]
	ds_read_b64_tr_b16 v[80:81], v243 offset:53248
	ds_read_b64_tr_b16 v[82:83], v243 offset:53760
	v_mfma_f32_32x32x16_bf16 v[0:15], v[164:167], v[84:87], v[0:15]
	ds_read_b64_tr_b16 v[84:85], v243 offset:50176
	ds_read_b64_tr_b16 v[86:87], v243 offset:50688
	v_mfma_f32_32x32x16_bf16 v[16:31], v[164:167], v[88:91], v[16:31]
	ds_read_b64_tr_b16 v[88:89], v243 offset:54272
	ds_read_b64_tr_b16 v[90:91], v243 offset:54784
	s_waitcnt lgkmcnt(8)
	v_mfma_f32_32x32x16_bf16 v[0:15], v[168:171], v[92:95], v[0:15]
	ds_read_b64_tr_b16 v[92:93], v243 offset:51200
	ds_read_b64_tr_b16 v[94:95], v243 offset:51712
	v_mfma_f32_32x32x16_bf16 v[16:31], v[168:171], v[96:99], v[16:31]
	ds_read_b64_tr_b16 v[96:97], v243 offset:55296
	ds_read_b64_tr_b16 v[98:99], v243 offset:55808
	v_mfma_f32_32x32x16_bf16 v[0:15], v[172:175], v[100:103], v[0:15]
	ds_read_b64_tr_b16 v[100:101], v243 offset:52224
	ds_read_b64_tr_b16 v[102:103], v243 offset:52736
	v_mfma_f32_32x32x16_bf16 v[16:31], v[172:175], v[104:107], v[16:31]
	ds_read_b64_tr_b16 v[104:105], v243 offset:56320
	ds_read_b64_tr_b16 v[106:107], v243 offset:56832
	s_waitcnt lgkmcnt(8)
	v_mfma_f32_32x32x16_bf16 v[32:47], v[160:163], v[214:217], v[32:47]
	v_mfma_f32_32x32x16_bf16 v[48:63], v[160:163], v[80:83], v[48:63]
	v_mfma_f32_32x32x16_bf16 v[32:47], v[164:167], v[84:87], v[32:47]
	v_mfma_f32_32x32x16_bf16 v[48:63], v[164:167], v[88:91], v[48:63]
	s_waitcnt lgkmcnt(0)
	v_mfma_f32_32x32x16_bf16 v[32:47], v[168:171], v[92:95], v[32:47]
	v_mfma_f32_32x32x16_bf16 v[48:63], v[168:171], v[96:99], v[48:63]
	v_mfma_f32_32x32x16_bf16 v[32:47], v[172:175], v[100:103], v[32:47]
	v_mfma_f32_32x32x16_bf16 v[48:63], v[172:175], v[104:107], v[48:63]
	s_branch .Lat_T1_end

; #define SBAR() __builtin_amdgcn_sched_barrier(0)
;   #define RESC() do{ if(resc){ asm volatile("s_waitcnt lgkmcnt(0)":::"memory"); \
;       _Pragma("unroll") for(int d_=0;d_<2;++d_) _Pragma("unroll") for(int r=0;r<16;++r)o[d_][r]*=wsf[crow(r,hi)]; } }while(0)
;   #define PKW(P,B) cvtpk_s(P[B],P[B+1])
; __device__ __forceinline__ void pv(f32x16*o,int vb,bf16x8 pa0,bf16x8 pa1,bf16x8 pa2,bf16x8 pa3){
;   #pragma unroll
;   for(int d0=0;d0<2;++d0){s16x4 lo[4],hi[4];
;     #pragma unroll
;     for(int ks=0;ks<4;++ks){
;       asm volatile("ds_read_b64_tr_b16 %0,%1 offset:%c2":"=&v"(lo[ks]):"v"(vb),"i"(d0*4096+ks*1024):"memory");
;       asm volatile("ds_read_b64_tr_b16 %0,%1 offset:%c2":"=&v"(hi[ks]):"v"(vb),"i"(d0*4096+ks*1024+512):"memory");}
;     asm volatile("s_waitcnt lgkmcnt(0)":::"memory");SBAR();
;     ...
;     o[d0]=__builtin_amdgcn_mfma_f32_32x32x16_bf16(pa0,PK(0),o[d0],0,0,0);
;     o[d0]=__builtin_amdgcn_mfma_f32_32x32x16_bf16(pa1,PK(1),o[d0],0,0,0);
;     o[d0]=__builtin_amdgcn_mfma_f32_32x32x16_bf16(pa2,PK(2),o[d0],0,0,0);
;     o[d0]=__builtin_amdgcn_mfma_f32_32x32x16_bf16(pa3,PK(3),o[d0],0,0,0);
;     ...
;   }
; }
; template<int THRL> __device__ __forceinline__ void attn_unit(int b,int qc,int vc,int qb,const bf16*Q,const bf16*__restrict__ K,const bf16*__restrict__ V,bf16*O,char*shm,const int tid){
;     ...
;   STEP(pB0,pB1,pA0,pA1,NT-1,false,false,false); RESC();
;   { float sacc=pB0[0]+pB0[1]; _Pragma("unroll") for(int r=2;r<16;++r)sacc+=pB0[r]; _Pragma("unroll") for(int r=0;r<16;++r)sacc+=pB1[r]; l_reg+=sacc;
;     pw0=(u32x4){PKW(pB0,0),PKW(pB0,2),PKW(pB0,4),PKW(pB0,6)};pw1=(u32x4){PKW(pB0,8),PKW(pB0,10),PKW(pB0,12),PKW(pB0,14)};pw2=(u32x4){PKW(pB1,0),PKW(pB1,2),PKW(pB1,4),PKW(pB1,6)};pw3=(u32x4){PKW(pB1,8),PKW(pB1,10),PKW(pB1,12),PKW(pB1,14)};
;     SBAR(); pv(o,vb0+sl_cur,PAF(0),PAF(1),PAF(2),PAF(3)); }
.Lat_drain:
	v_add_u32_e32 v243, s17, v204
	v_add_f32_e32 v245, v112, v113
	v_add_f32_e32 v246, v114, v115
	v_add_f32_e32 v245, v116, v245
	v_add_f32_e32 v246, v117, v246
	v_cvt_pk_bf16_f32 v160, v112, v113
	v_cvt_pk_bf16_f32 v161, v114, v115
	v_add_f32_e32 v245, v118, v245
	v_add_f32_e32 v246, v119, v246
	v_add_f32_e32 v245, v120, v245
	v_add_f32_e32 v246, v121, v246
	v_cvt_pk_bf16_f32 v162, v116, v117
	v_cvt_pk_bf16_f32 v163, v118, v119
	v_add_f32_e32 v245, v122, v245
	v_add_f32_e32 v246, v123, v246
	v_add_f32_e32 v245, v124, v245
	v_add_f32_e32 v246, v125, v246
	v_cvt_pk_bf16_f32 v164, v120, v121
	v_cvt_pk_bf16_f32 v165, v122, v123
	v_add_f32_e32 v245, v126, v245
	v_add_f32_e32 v246, v127, v246
	v_add_f32_e32 v245, v128, v245
	v_add_f32_e32 v246, v129, v246
	v_cvt_pk_bf16_f32 v166, v124, v125
	v_cvt_pk_bf16_f32 v167, v126, v127
	v_add_f32_e32 v245, v130, v245
	v_add_f32_e32 v246, v131, v246
	v_add_f32_e32 v245, v132, v245
	v_add_f32_e32 v246, v133, v246
	v_cvt_pk_bf16_f32 v168, v128, v129
	v_cvt_pk_bf16_f32 v169, v130, v131
	v_add_f32_e32 v245, v134, v245
	v_add_f32_e32 v246, v135, v246
	v_add_f32_e32 v245, v136, v245
	v_add_f32_e32 v246, v137, v246
	v_cvt_pk_bf16_f32 v170, v132, v133
	v_cvt_pk_bf16_f32 v171, v134, v135
	v_add_f32_e32 v245, v138, v245
	v_add_f32_e32 v246, v139, v246
	v_add_f32_e32 v245, v140, v245
	v_add_f32_e32 v246, v141, v246
	v_cvt_pk_bf16_f32 v172, v136, v137
	v_cvt_pk_bf16_f32 v173, v138, v139
	v_add_f32_e32 v245, v142, v245
	v_add_f32_e32 v246, v143, v246
	v_add_f32_e32 v245, v245, v246
	v_cvt_pk_bf16_f32 v174, v140, v141
	v_cvt_pk_bf16_f32 v175, v142, v143
	v_add_f32_e32 v211, v211, v245
	ds_read_b64_tr_b16 v[112:113], v243 offset:24576
	ds_read_b64_tr_b16 v[114:115], v243 offset:25088
	ds_read_b64_tr_b16 v[116:117], v243 offset:28672
	ds_read_b64_tr_b16 v[118:119], v243 offset:29184
	ds_read_b64_tr_b16 v[120:121], v243 offset:25600
	ds_read_b64_tr_b16 v[122:123], v243 offset:26112
	ds_read_b64_tr_b16 v[124:125], v243 offset:29696
	ds_read_b64_tr_b16 v[126:127], v243 offset:30208
	ds_read_b64_tr_b16 v[128:129], v243 offset:26624
	ds_read_b64_tr_b16 v[130:131], v243 offset:27136
	ds_read_b64_tr_b16 v[132:133], v243 offset:30720
	ds_read_b64_tr_b16 v[134:135], v243 offset:31232
	ds_read_b64_tr_b16 v[136:137], v243 offset:27648
	ds_read_b64_tr_b16 v[138:139], v243 offset:28160
	ds_read_b64_tr_b16 v[140:141], v243 offset:31744
	ds_read_b64_tr_b16 v[142:143], v243 offset:32256
	s_waitcnt lgkmcnt(14)
	v_mfma_f32_32x32x16_bf16 v[0:15], v[160:163], v[112:115], v[0:15]
	s_waitcnt lgkmcnt(12)
	v_mfma_f32_32x32x16_bf16 v[16:31], v[160:163], v[116:119], v[16:31]
	s_waitcnt lgkmcnt(10)
	v_mfma_f32_32x32x16_bf16 v[0:15], v[164:167], v[120:123], v[0:15]
	s_waitcnt lgkmcnt(8)
	v_mfma_f32_32x32x16_bf16 v[16:31], v[164:167], v[124:127], v[16:31]
	s_waitcnt lgkmcnt(6)
	v_mfma_f32_32x32x16_bf16 v[0:15], v[168:171], v[128:131], v[0:15]
	s_waitcnt lgkmcnt(4)
	v_mfma_f32_32x32x16_bf16 v[16:31], v[168:171], v[132:135], v[16:31]
	s_waitcnt lgkmcnt(2)
	v_mfma_f32_32x32x16_bf16 v[0:15], v[172:175], v[136:139], v[0:15]
	s_waitcnt lgkmcnt(0)
	v_mfma_f32_32x32x16_bf16 v[16:31], v[172:175], v[140:143], v[16:31]
	ds_read_b64_tr_b16 v[112:113], v243 offset:49152
	ds_read_b64_tr_b16 v[114:115], v243 offset:49664
	ds_read_b64_tr_b16 v[116:117], v243 offset:53248
	ds_read_b64_tr_b16 v[118:119], v243 offset:53760
	ds_read_b64_tr_b16 v[120:121], v243 offset:50176
	ds_read_b64_tr_b16 v[122:123], v243 offset:50688
	ds_read_b64_tr_b16 v[124:125], v243 offset:54272
	ds_read_b64_tr_b16 v[126:127], v243 offset:54784
	ds_read_b64_tr_b16 v[128:129], v243 offset:51200
	ds_read_b64_tr_b16 v[130:131], v243 offset:51712
	ds_read_b64_tr_b16 v[132:133], v243 offset:55296
	ds_read_b64_tr_b16 v[134:135], v243 offset:55808
	ds_read_b64_tr_b16 v[136:137], v243 offset:52224
	ds_read_b64_tr_b16 v[138:139], v243 offset:52736
	ds_read_b64_tr_b16 v[140:141], v243 offset:56320
	ds_read_b64_tr_b16 v[142:143], v243 offset:56832
	s_waitcnt lgkmcnt(14)
	v_mfma_f32_32x32x16_bf16 v[32:47], v[160:163], v[112:115], v[32:47]
	s_waitcnt lgkmcnt(12)
	v_mfma_f32_32x32x16_bf16 v[48:63], v[160:163], v[116:119], v[48:63]
	s_waitcnt lgkmcnt(10)
	v_mfma_f32_32x32x16_bf16 v[32:47], v[164:167], v[120:123], v[32:47]
	s_waitcnt lgkmcnt(8)
	v_mfma_f32_32x32x16_bf16 v[48:63], v[164:167], v[124:127], v[48:63]
	s_waitcnt lgkmcnt(6)
	v_mfma_f32_32x32x16_bf16 v[32:47], v[168:171], v[128:131], v[32:47]
	s_waitcnt lgkmcnt(4)
	v_mfma_f32_32x32x16_bf16 v[48:63], v[168:171], v[132:135], v[48:63]
	s_waitcnt lgkmcnt(2)
	v_mfma_f32_32x32x16_bf16 v[32:47], v[172:175], v[136:139], v[32:47]
	s_waitcnt lgkmcnt(0)
	v_mfma_f32_32x32x16_bf16 v[48:63], v[172:175], v[140:143], v[48:63]

.Lat_resc_M1:
	s_waitcnt lgkmcnt(0)
	ds_read_b128 v[214:217], v227 offset:0
	s_waitcnt lgkmcnt(0)
	v_pk_mul_f32 v[0:1], v[0:1], v[214:215]
	v_pk_mul_f32 v[2:3], v[2:3], v[216:217]
	v_pk_mul_f32 v[16:17], v[16:17], v[214:215]
	v_pk_mul_f32 v[18:19], v[18:19], v[216:217]
	v_pk_mul_f32 v[32:33], v[32:33], v[214:215]
	v_pk_mul_f32 v[34:35], v[34:35], v[216:217]
	v_pk_mul_f32 v[48:49], v[48:49], v[214:215]
	v_pk_mul_f32 v[50:51], v[50:51], v[216:217]
	ds_read_b128 v[214:217], v227 offset:32
	s_waitcnt lgkmcnt(0)
	v_pk_mul_f32 v[4:5], v[4:5], v[214:215]
	v_pk_mul_f32 v[6:7], v[6:7], v[216:217]
	v_pk_mul_f32 v[20:21], v[20:21], v[214:215]
	v_pk_mul_f32 v[22:23], v[22:23], v[216:217]
	v_pk_mul_f32 v[36:37], v[36:37], v[214:215]
	v_pk_mul_f32 v[38:39], v[38:39], v[216:217]
	v_pk_mul_f32 v[52:53], v[52:53], v[214:215]
	v_pk_mul_f32 v[54:55], v[54:55], v[216:217]
	ds_read_b128 v[214:217], v227 offset:64
	s_waitcnt lgkmcnt(0)
	v_pk_mul_f32 v[8:9], v[8:9], v[214:215]
	v_pk_mul_f32 v[10:11], v[10:11], v[216:217]
	v_pk_mul_f32 v[24:25], v[24:25], v[214:215]
	v_pk_mul_f32 v[26:27], v[26:27], v[216:217]
	v_pk_mul_f32 v[40:41], v[40:41], v[214:215]
	v_pk_mul_f32 v[42:43], v[42:43], v[216:217]
	v_pk_mul_f32 v[56:57], v[56:57], v[214:215]
	v_pk_mul_f32 v[58:59], v[58:59], v[216:217]
	ds_read_b128 v[214:217], v227 offset:96
	s_waitcnt lgkmcnt(0)
	v_pk_mul_f32 v[12:13], v[12:13], v[214:215]
	v_pk_mul_f32 v[14:15], v[14:15], v[216:217]
	v_pk_mul_f32 v[28:29], v[28:29], v[214:215]
	v_pk_mul_f32 v[30:31], v[30:31], v[216:217]
	v_pk_mul_f32 v[44:45], v[44:45], v[214:215]
	v_pk_mul_f32 v[46:47], v[46:47], v[216:217]
	v_pk_mul_f32 v[60:61], v[60:61], v[214:215]
	v_pk_mul_f32 v[62:63], v[62:63], v[216:217]
	s_branch .Lat_noresc_M1
